# 4-slot ring k-loops with fragment reads issued in pairs (two ds_read_b128 per MFMA gap)
# baseline (speedup 1.0000x reference)
.Lk_ffo:
	s_waitcnt lgkmcnt(0)
	v_mfma_f32_16x16x32_bf16 v[92:95], v[166:169], v[134:137], v[92:95]
	s_waitcnt vmcnt(10)
	s_barrier
	v_mfma_f32_16x16x32_bf16 v[88:91], v[200:203], v[134:137], v[88:91]
	s_cmp_eq_u32 s35, 0xf000
	s_cselect_b32 s38, s37, s36
	s_add_u32 s39, s34, s35
	v_mfma_f32_16x16x32_bf16 v[84:87], v[204:207], v[134:137], v[84:87]
	v_add_u32_e32 v170, s38, v170
	v_add_u32_e32 v172, s38, v172
	s_add_u32 s35, s35, s38
	v_mfma_f32_16x16x32_bf16 v[80:83], v[208:211], v[134:137], v[80:83]
	ds_read_b128 v[212:215], v170
	ds_read_b128 v[216:219], v170 offset:1024
	v_mfma_f32_16x16x32_bf16 v[76:79], v[166:169], v[138:141], v[76:79]
	ds_read_b128 v[220:223], v170 offset:2048
	ds_read_b128 v[224:227], v170 offset:3072
	v_mfma_f32_16x16x32_bf16 v[72:75], v[200:203], v[138:141], v[72:75]
	ds_read_b128 v[228:231], v170 offset:4096
	ds_read_b128 v[232:235], v170 offset:5120
	v_mfma_f32_16x16x32_bf16 v[68:71], v[204:207], v[138:141], v[68:71]
	ds_read_b128 v[244:247], v172 offset:12288
	ds_read_b128 v[248:251], v172 offset:13312
	v_mfma_f32_16x16x32_bf16 v[64:67], v[208:211], v[138:141], v[64:67]
	ds_read_b128 v[252:255], v172 offset:14336
	ds_read_b128 v[116:119], v172 offset:15360
	v_mfma_f32_16x16x32_bf16 v[60:63], v[166:169], v[150:153], v[60:63]
	s_mov_b32 m0, s39
	v_mfma_f32_16x16x32_bf16 v[56:59], v[200:203], v[150:153], v[56:59]
	global_load_lds_dwordx4 v[124:125], off
	v_lshl_add_u64 v[124:125], v[124:125], 0, 64
	v_mfma_f32_16x16x32_bf16 v[52:55], v[204:207], v[150:153], v[52:55]
	s_add_u32 m0, s39, 0x1000
	v_mfma_f32_16x16x32_bf16 v[48:51], v[208:211], v[150:153], v[48:51]
	global_load_lds_dwordx4 v[122:123], off
	v_lshl_add_u64 v[122:123], v[122:123], 0, 64
	v_mfma_f32_16x16x32_bf16 v[44:47], v[166:169], v[154:157], v[44:47]
	s_add_u32 m0, s39, 0x2000
	v_mfma_f32_16x16x32_bf16 v[40:43], v[200:203], v[154:157], v[40:43]
	global_load_lds_dwordx4 v[120:121], off
	v_lshl_add_u64 v[120:121], v[120:121], 0, 64
	v_mfma_f32_16x16x32_bf16 v[36:39], v[204:207], v[154:157], v[36:39]
	s_add_u32 m0, s39, 0x3000
	v_mfma_f32_16x16x32_bf16 v[32:35], v[208:211], v[154:157], v[32:35]
	global_load_lds_dwordx4 v[236:237], off
	v_lshl_add_u64 v[236:237], v[236:237], 0, 64
	v_mfma_f32_16x16x32_bf16 v[28:31], v[166:169], v[158:161], v[28:31]
	s_add_u32 m0, s39, 0x4000
	v_mfma_f32_16x16x32_bf16 v[24:27], v[200:203], v[158:161], v[24:27]
	global_load_lds_dwordx4 v[126:127], off
	v_lshl_add_u64 v[126:127], v[126:127], 0, 64
	v_mfma_f32_16x16x32_bf16 v[20:23], v[204:207], v[158:161], v[20:23]
	v_mfma_f32_16x16x32_bf16 v[16:19], v[208:211], v[158:161], v[16:19]
	v_mfma_f32_16x16x32_bf16 v[8:11], v[166:169], v[162:165], v[8:11]
	v_mfma_f32_16x16x32_bf16 v[4:7], v[200:203], v[162:165], v[4:7]
	v_mfma_f32_16x16x32_bf16 v[12:15], v[204:207], v[162:165], v[12:15]
	v_mfma_f32_16x16x32_bf16 v[0:3], v[208:211], v[162:165], v[0:3]
	s_waitcnt lgkmcnt(0)
	v_mfma_f32_16x16x32_bf16 v[92:95], v[244:247], v[212:215], v[92:95]
	s_waitcnt vmcnt(10)
	s_barrier
	v_mfma_f32_16x16x32_bf16 v[88:91], v[248:251], v[212:215], v[88:91]
	s_cmp_eq_u32 s35, 0xf000
	s_cselect_b32 s38, s37, s36
	s_add_u32 s39, s34, s35
	v_mfma_f32_16x16x32_bf16 v[84:87], v[252:255], v[212:215], v[84:87]
	v_add_u32_e32 v170, s38, v170
	v_add_u32_e32 v172, s38, v172
	s_add_u32 s35, s35, s38
	v_mfma_f32_16x16x32_bf16 v[80:83], v[116:119], v[212:215], v[80:83]
	ds_read_b128 v[134:137], v170
	ds_read_b128 v[138:141], v170 offset:1024
	v_mfma_f32_16x16x32_bf16 v[76:79], v[244:247], v[216:219], v[76:79]
	ds_read_b128 v[150:153], v170 offset:2048
	ds_read_b128 v[154:157], v170 offset:3072
	v_mfma_f32_16x16x32_bf16 v[72:75], v[248:251], v[216:219], v[72:75]
	ds_read_b128 v[158:161], v170 offset:4096
	ds_read_b128 v[162:165], v170 offset:5120
	v_mfma_f32_16x16x32_bf16 v[68:71], v[252:255], v[216:219], v[68:71]
	ds_read_b128 v[166:169], v172 offset:12288
	ds_read_b128 v[200:203], v172 offset:13312
	v_mfma_f32_16x16x32_bf16 v[64:67], v[116:119], v[216:219], v[64:67]
	ds_read_b128 v[204:207], v172 offset:14336
	ds_read_b128 v[208:211], v172 offset:15360
	v_mfma_f32_16x16x32_bf16 v[60:63], v[244:247], v[220:223], v[60:63]
	s_mov_b32 m0, s39
	v_mfma_f32_16x16x32_bf16 v[56:59], v[248:251], v[220:223], v[56:59]
	global_load_lds_dwordx4 v[124:125], off
	v_lshl_add_u64 v[124:125], v[124:125], 0, 64
	v_mfma_f32_16x16x32_bf16 v[52:55], v[252:255], v[220:223], v[52:55]
	s_add_u32 m0, s39, 0x1000
	v_mfma_f32_16x16x32_bf16 v[48:51], v[116:119], v[220:223], v[48:51]
	global_load_lds_dwordx4 v[122:123], off
	v_lshl_add_u64 v[122:123], v[122:123], 0, 64
	v_mfma_f32_16x16x32_bf16 v[44:47], v[244:247], v[224:227], v[44:47]
	s_add_u32 m0, s39, 0x2000
	v_mfma_f32_16x16x32_bf16 v[40:43], v[248:251], v[224:227], v[40:43]
	global_load_lds_dwordx4 v[120:121], off
	v_lshl_add_u64 v[120:121], v[120:121], 0, 64
	v_mfma_f32_16x16x32_bf16 v[36:39], v[252:255], v[224:227], v[36:39]
	s_add_u32 m0, s39, 0x3000
	v_mfma_f32_16x16x32_bf16 v[32:35], v[116:119], v[224:227], v[32:35]
	global_load_lds_dwordx4 v[236:237], off
	v_lshl_add_u64 v[236:237], v[236:237], 0, 64
	v_mfma_f32_16x16x32_bf16 v[28:31], v[244:247], v[228:231], v[28:31]
	s_add_u32 m0, s39, 0x4000
	v_mfma_f32_16x16x32_bf16 v[24:27], v[248:251], v[228:231], v[24:27]
	global_load_lds_dwordx4 v[126:127], off
	v_lshl_add_u64 v[126:127], v[126:127], 0, 64
	v_mfma_f32_16x16x32_bf16 v[20:23], v[252:255], v[228:231], v[20:23]
	s_add_i32 s41, s41, -1
	s_cmp_eq_u32 s41, 0
	v_mfma_f32_16x16x32_bf16 v[16:19], v[116:119], v[228:231], v[16:19]
	v_mfma_f32_16x16x32_bf16 v[8:11], v[244:247], v[232:235], v[8:11]
	v_mfma_f32_16x16x32_bf16 v[4:7], v[248:251], v[232:235], v[4:7]
	v_mfma_f32_16x16x32_bf16 v[12:15], v[252:255], v[232:235], v[12:15]
	v_mfma_f32_16x16x32_bf16 v[0:3], v[116:119], v[232:235], v[0:3]
	s_cbranch_scc0 .Lk_ffo
	s_waitcnt lgkmcnt(0)
	v_mfma_f32_16x16x32_bf16 v[92:95], v[166:169], v[134:137], v[92:95]
	s_waitcnt vmcnt(10)
	s_barrier
	v_mfma_f32_16x16x32_bf16 v[88:91], v[200:203], v[134:137], v[88:91]
	s_cmp_eq_u32 s35, 0xf000
	s_cselect_b32 s38, s37, s36
	v_mfma_f32_16x16x32_bf16 v[84:87], v[204:207], v[134:137], v[84:87]
	v_add_u32_e32 v170, s38, v170
	v_add_u32_e32 v172, s38, v172
	s_add_u32 s35, s35, s38
	v_mfma_f32_16x16x32_bf16 v[80:83], v[208:211], v[134:137], v[80:83]
	ds_read_b128 v[212:215], v170
	ds_read_b128 v[216:219], v170 offset:1024
	v_mfma_f32_16x16x32_bf16 v[76:79], v[166:169], v[138:141], v[76:79]
	ds_read_b128 v[220:223], v170 offset:2048
	ds_read_b128 v[224:227], v170 offset:3072
	v_mfma_f32_16x16x32_bf16 v[72:75], v[200:203], v[138:141], v[72:75]
	ds_read_b128 v[228:231], v170 offset:4096
	ds_read_b128 v[232:235], v170 offset:5120
	v_mfma_f32_16x16x32_bf16 v[68:71], v[204:207], v[138:141], v[68:71]
	ds_read_b128 v[244:247], v172 offset:12288
	ds_read_b128 v[248:251], v172 offset:13312
	v_mfma_f32_16x16x32_bf16 v[64:67], v[208:211], v[138:141], v[64:67]
	ds_read_b128 v[252:255], v172 offset:14336
	ds_read_b128 v[116:119], v172 offset:15360
	v_mfma_f32_16x16x32_bf16 v[60:63], v[166:169], v[150:153], v[60:63]
	v_mfma_f32_16x16x32_bf16 v[56:59], v[200:203], v[150:153], v[56:59]
	v_mfma_f32_16x16x32_bf16 v[52:55], v[204:207], v[150:153], v[52:55]
	v_mfma_f32_16x16x32_bf16 v[48:51], v[208:211], v[150:153], v[48:51]
	v_mfma_f32_16x16x32_bf16 v[44:47], v[166:169], v[154:157], v[44:47]
	v_mfma_f32_16x16x32_bf16 v[40:43], v[200:203], v[154:157], v[40:43]
	v_mfma_f32_16x16x32_bf16 v[36:39], v[204:207], v[154:157], v[36:39]
	v_mfma_f32_16x16x32_bf16 v[32:35], v[208:211], v[154:157], v[32:35]
	v_mfma_f32_16x16x32_bf16 v[28:31], v[166:169], v[158:161], v[28:31]
	v_mfma_f32_16x16x32_bf16 v[24:27], v[200:203], v[158:161], v[24:27]
	v_mfma_f32_16x16x32_bf16 v[20:23], v[204:207], v[158:161], v[20:23]
	v_mfma_f32_16x16x32_bf16 v[16:19], v[208:211], v[158:161], v[16:19]
	v_mfma_f32_16x16x32_bf16 v[8:11], v[166:169], v[162:165], v[8:11]
	v_mfma_f32_16x16x32_bf16 v[4:7], v[200:203], v[162:165], v[4:7]
	v_mfma_f32_16x16x32_bf16 v[12:15], v[204:207], v[162:165], v[12:15]
	v_mfma_f32_16x16x32_bf16 v[0:3], v[208:211], v[162:165], v[0:3]
	s_waitcnt lgkmcnt(0)
	v_mfma_f32_16x16x32_bf16 v[92:95], v[244:247], v[212:215], v[92:95]
	s_waitcnt vmcnt(5)
	s_barrier
	v_mfma_f32_16x16x32_bf16 v[88:91], v[248:251], v[212:215], v[88:91]
	s_cmp_eq_u32 s35, 0xf000
	s_cselect_b32 s38, s37, s36
	v_mfma_f32_16x16x32_bf16 v[84:87], v[252:255], v[212:215], v[84:87]
	v_add_u32_e32 v170, s38, v170
	v_add_u32_e32 v172, s38, v172
	s_add_u32 s35, s35, s38
	v_mfma_f32_16x16x32_bf16 v[80:83], v[116:119], v[212:215], v[80:83]
	ds_read_b128 v[134:137], v170
	ds_read_b128 v[138:141], v170 offset:1024
	v_mfma_f32_16x16x32_bf16 v[76:79], v[244:247], v[216:219], v[76:79]
	ds_read_b128 v[150:153], v170 offset:2048
	ds_read_b128 v[154:157], v170 offset:3072
	v_mfma_f32_16x16x32_bf16 v[72:75], v[248:251], v[216:219], v[72:75]
	ds_read_b128 v[158:161], v170 offset:4096
	ds_read_b128 v[162:165], v170 offset:5120
	v_mfma_f32_16x16x32_bf16 v[68:71], v[252:255], v[216:219], v[68:71]
	ds_read_b128 v[166:169], v172 offset:12288
	ds_read_b128 v[200:203], v172 offset:13312
	v_mfma_f32_16x16x32_bf16 v[64:67], v[116:119], v[216:219], v[64:67]
	ds_read_b128 v[204:207], v172 offset:14336
	ds_read_b128 v[208:211], v172 offset:15360
	v_mfma_f32_16x16x32_bf16 v[60:63], v[244:247], v[220:223], v[60:63]
	v_mfma_f32_16x16x32_bf16 v[56:59], v[248:251], v[220:223], v[56:59]
	v_mfma_f32_16x16x32_bf16 v[52:55], v[252:255], v[220:223], v[52:55]
	v_mfma_f32_16x16x32_bf16 v[48:51], v[116:119], v[220:223], v[48:51]
	v_mfma_f32_16x16x32_bf16 v[44:47], v[244:247], v[224:227], v[44:47]
	v_mfma_f32_16x16x32_bf16 v[40:43], v[248:251], v[224:227], v[40:43]
	v_mfma_f32_16x16x32_bf16 v[36:39], v[252:255], v[224:227], v[36:39]
	v_mfma_f32_16x16x32_bf16 v[32:35], v[116:119], v[224:227], v[32:35]
	v_mfma_f32_16x16x32_bf16 v[28:31], v[244:247], v[228:231], v[28:31]
	v_mfma_f32_16x16x32_bf16 v[24:27], v[248:251], v[228:231], v[24:27]
	v_mfma_f32_16x16x32_bf16 v[20:23], v[252:255], v[228:231], v[20:23]
	v_mfma_f32_16x16x32_bf16 v[16:19], v[116:119], v[228:231], v[16:19]
	v_mfma_f32_16x16x32_bf16 v[8:11], v[244:247], v[232:235], v[8:11]
	v_mfma_f32_16x16x32_bf16 v[4:7], v[248:251], v[232:235], v[4:7]
	v_mfma_f32_16x16x32_bf16 v[12:15], v[252:255], v[232:235], v[12:15]
	v_mfma_f32_16x16x32_bf16 v[0:3], v[116:119], v[232:235], v[0:3]
	s_waitcnt lgkmcnt(0)
	v_mfma_f32_16x16x32_bf16 v[92:95], v[166:169], v[134:137], v[92:95]
	s_waitcnt vmcnt(0)
	s_barrier
	v_mfma_f32_16x16x32_bf16 v[88:91], v[200:203], v[134:137], v[88:91]
	s_cmp_eq_u32 s35, 0xf000
	s_cselect_b32 s38, s37, s36
	v_mfma_f32_16x16x32_bf16 v[84:87], v[204:207], v[134:137], v[84:87]
	v_add_u32_e32 v170, s38, v170
	v_add_u32_e32 v172, s38, v172
	s_add_u32 s35, s35, s38
	v_mfma_f32_16x16x32_bf16 v[80:83], v[208:211], v[134:137], v[80:83]
	ds_read_b128 v[212:215], v170
	ds_read_b128 v[216:219], v170 offset:1024
	v_mfma_f32_16x16x32_bf16 v[76:79], v[166:169], v[138:141], v[76:79]
	ds_read_b128 v[220:223], v170 offset:2048
	ds_read_b128 v[224:227], v170 offset:3072
	v_mfma_f32_16x16x32_bf16 v[72:75], v[200:203], v[138:141], v[72:75]
	ds_read_b128 v[228:231], v170 offset:4096
	ds_read_b128 v[232:235], v170 offset:5120
	v_mfma_f32_16x16x32_bf16 v[68:71], v[204:207], v[138:141], v[68:71]
	ds_read_b128 v[244:247], v172 offset:12288
	ds_read_b128 v[248:251], v172 offset:13312
	v_mfma_f32_16x16x32_bf16 v[64:67], v[208:211], v[138:141], v[64:67]
	ds_read_b128 v[252:255], v172 offset:14336
	ds_read_b128 v[116:119], v172 offset:15360
	v_mfma_f32_16x16x32_bf16 v[60:63], v[166:169], v[150:153], v[60:63]
	v_mfma_f32_16x16x32_bf16 v[56:59], v[200:203], v[150:153], v[56:59]
	v_mfma_f32_16x16x32_bf16 v[52:55], v[204:207], v[150:153], v[52:55]
	v_mfma_f32_16x16x32_bf16 v[48:51], v[208:211], v[150:153], v[48:51]
	v_mfma_f32_16x16x32_bf16 v[44:47], v[166:169], v[154:157], v[44:47]
	v_mfma_f32_16x16x32_bf16 v[40:43], v[200:203], v[154:157], v[40:43]
	v_mfma_f32_16x16x32_bf16 v[36:39], v[204:207], v[154:157], v[36:39]
	v_mfma_f32_16x16x32_bf16 v[32:35], v[208:211], v[154:157], v[32:35]
	v_mfma_f32_16x16x32_bf16 v[28:31], v[166:169], v[158:161], v[28:31]
	v_mfma_f32_16x16x32_bf16 v[24:27], v[200:203], v[158:161], v[24:27]
	v_mfma_f32_16x16x32_bf16 v[20:23], v[204:207], v[158:161], v[20:23]
	v_mfma_f32_16x16x32_bf16 v[16:19], v[208:211], v[158:161], v[16:19]
	v_mfma_f32_16x16x32_bf16 v[8:11], v[166:169], v[162:165], v[8:11]
	v_mfma_f32_16x16x32_bf16 v[4:7], v[200:203], v[162:165], v[4:7]
	v_mfma_f32_16x16x32_bf16 v[12:15], v[204:207], v[162:165], v[12:15]
	v_mfma_f32_16x16x32_bf16 v[0:3], v[208:211], v[162:165], v[0:3]
	s_waitcnt lgkmcnt(0)
	v_mfma_f32_16x16x32_bf16 v[92:95], v[244:247], v[212:215], v[92:95]
	v_mfma_f32_16x16x32_bf16 v[88:91], v[248:251], v[212:215], v[88:91]
	v_mfma_f32_16x16x32_bf16 v[84:87], v[252:255], v[212:215], v[84:87]
	v_mfma_f32_16x16x32_bf16 v[80:83], v[116:119], v[212:215], v[80:83]
	v_mfma_f32_16x16x32_bf16 v[76:79], v[244:247], v[216:219], v[76:79]
	v_mfma_f32_16x16x32_bf16 v[72:75], v[248:251], v[216:219], v[72:75]
	v_mfma_f32_16x16x32_bf16 v[68:71], v[252:255], v[216:219], v[68:71]
	v_mfma_f32_16x16x32_bf16 v[64:67], v[116:119], v[216:219], v[64:67]
	v_mfma_f32_16x16x32_bf16 v[60:63], v[244:247], v[220:223], v[60:63]
	v_mfma_f32_16x16x32_bf16 v[56:59], v[248:251], v[220:223], v[56:59]
	v_mfma_f32_16x16x32_bf16 v[52:55], v[252:255], v[220:223], v[52:55]
	v_mfma_f32_16x16x32_bf16 v[48:51], v[116:119], v[220:223], v[48:51]
	v_mfma_f32_16x16x32_bf16 v[44:47], v[244:247], v[224:227], v[44:47]
	v_mfma_f32_16x16x32_bf16 v[40:43], v[248:251], v[224:227], v[40:43]
	v_mfma_f32_16x16x32_bf16 v[36:39], v[252:255], v[224:227], v[36:39]
	v_mfma_f32_16x16x32_bf16 v[32:35], v[116:119], v[224:227], v[32:35]
	v_mfma_f32_16x16x32_bf16 v[28:31], v[244:247], v[228:231], v[28:31]
	v_mfma_f32_16x16x32_bf16 v[24:27], v[248:251], v[228:231], v[24:27]
	v_mfma_f32_16x16x32_bf16 v[20:23], v[252:255], v[228:231], v[20:23]
	v_mfma_f32_16x16x32_bf16 v[16:19], v[116:119], v[228:231], v[16:19]
	v_mfma_f32_16x16x32_bf16 v[8:11], v[244:247], v[232:235], v[8:11]
	v_mfma_f32_16x16x32_bf16 v[4:7], v[248:251], v[232:235], v[4:7]
	v_mfma_f32_16x16x32_bf16 v[12:15], v[252:255], v[232:235], v[12:15]
	v_mfma_f32_16x16x32_bf16 v[0:3], v[116:119], v[232:235], v[0:3]
	s_barrier
	v_mov_b32_e32 v170, s46
	v_mov_b32_e32 v172, s47
	ds_write_b32 v183, v170
	ds_write_b32 v184, v172
	s_waitcnt lgkmcnt(0)
	s_mulk_i32 s7, 0xc0
	s_add_i32 s5, s5, s51
	v_readlane_b32 s10, v242, 27
	v_readlane_b32 s11, v242, 28
	v_readlane_b32 s12, v242, 25
	v_readlane_b32 s13, v242, 26
	v_readlane_b32 s14, v243, 11
	v_readlane_b32 s15, v243, 12
	s_mov_b32 s8, 0x3fd744fd
	v_add_u32_e32 v236, s7, v145
	v_or_b32_e32 v254, s6, v146
	v_mov_b32_e32 v255, 0
	v_or_b32_e32 v237, v236, v133
	v_lshlrev_b64 v[254:255], 2, v[254:255]
	s_nop 0
	v_lshl_add_u64 v[250:251], s[12:13], 0, v[254:255]
	v_lshl_add_u64 v[252:253], s[14:15], 0, v[254:255]
	s_mov_b64 s[14:15], 0x5000
	v_lshl_add_u64 v[252:253], v[252:253], 0, s[14:15]
	v_readlane_b32 s12, v242, 29
	v_readlane_b32 s13, v242, 30
	v_lshl_add_u64 v[248:249], s[12:13], 0, v[254:255]
	v_readlane_b32 s12, v241, 9
	s_add_i32 s12, s12, -10
	s_mul_i32 s12, s12, 57
	s_lshr_b32 s12, s12, 9
	s_lshl_b32 s12, s12, 12
	v_readlane_b32 s14, v243, 59
	v_readlane_b32 s15, v243, 60
	s_add_u32 s14, s14, s12
	s_addc_u32 s15, s15, 0
	v_lshl_add_u64 v[224:225], s[14:15], 0, v[254:255]
	v_readlane_b32 s14, v243, 61
	v_readlane_b32 s15, v243, 62
	s_add_u32 s14, s14, s12
	s_addc_u32 s15, s15, 0
	v_lshl_add_u64 v[226:227], s[14:15], 0, v[254:255]
	global_load_dwordx4 v[96:99], v[224:225], off
	global_load_dwordx4 v[112:115], v[226:227], off
	global_load_dwordx4 v[100:103], v[224:225], off offset:64
	global_load_dwordx4 v[150:153], v[226:227], off offset:64
	global_load_dwordx4 v[104:107], v[224:225], off offset:128
	global_load_dwordx4 v[142:145], v[226:227], off offset:128
	global_load_dwordx4 v[108:111], v[224:225], off offset:192
	global_load_dwordx4 v[146:149], v[226:227], off offset:192
	v_mov_b32_e32 v255, 0
	v_add_u32_e32 v254, 0, v237
	v_add_u32_e32 v236, 0xfffff000, v254
	v_cmp_lt_i32_e32 vcc, 0xfff, v254
	v_lshrrev_b32_e32 v236, 10, v236
	v_lshlrev_b32_e32 v224, 3, v254
	v_lshlrev_b32_e32 v254, 12, v254
	v_add_u32_e32 v236, 1, v236
	v_mov_b32_e32 v225, 0
	v_cndmask_b32_e32 v236, 0, v236, vcc
	v_lshl_add_u64 v[224:225], v[224:225], 0, s[10:11]
	v_lshl_add_u64 v[228:229], v[254:255], 0, v[250:251]
	v_add_u32_e32 v236, s4, v236
	v_mad_i64_i32 v[232:233], s[0:1], v236, s33, v[252:253]
	global_load_dwordx2 v[132:133], v[224:225], off
	v_lshl_add_u64 v[224:225], v[254:255], 0, v[248:249]
	v_add_u32_e32 v254, 16, v237
	v_add_u32_e32 v236, 0xfffff000, v254
	v_cmp_lt_i32_e32 vcc, 0xfff, v254
	v_lshrrev_b32_e32 v236, 10, v236
	v_lshlrev_b32_e32 v226, 3, v254
	v_lshlrev_b32_e32 v254, 12, v254
	v_add_u32_e32 v236, 1, v236
	v_mov_b32_e32 v227, 0
	v_cndmask_b32_e32 v236, 0, v236, vcc
	v_lshl_add_u64 v[226:227], v[226:227], 0, s[10:11]
	v_lshl_add_u64 v[230:231], v[254:255], 0, v[250:251]
	v_add_u32_e32 v236, s4, v236
	v_mad_i64_i32 v[234:235], s[0:1], v236, s33, v[252:253]
	global_load_dword v128, v[226:227], off
	global_load_dword v170, v[226:227], off offset:4
	v_lshl_add_u64 v[226:227], v[254:255], 0, v[248:249]
	global_load_dwordx4 v[154:157], v[224:225], off
	global_load_dwordx4 v[116:119], v[232:233], off
	global_load_dwordx4 v[158:161], v[224:225], off offset:64
	global_load_dwordx4 v[120:123], v[232:233], off offset:64
	global_load_dwordx4 v[162:165], v[224:225], off offset:128
	global_load_dwordx4 v[124:127], v[232:233], off offset:128
	global_load_dwordx4 v[166:169], v[224:225], off offset:192
	global_load_dwordx4 v[134:137], v[232:233], off offset:192
	global_load_dwordx4 v[208:211], v[226:227], off
	global_load_dwordx4 v[138:141], v[234:235], off
	global_load_dwordx4 v[212:215], v[226:227], off offset:64
	global_load_dwordx4 v[200:203], v[234:235], off offset:64
	global_load_dwordx4 v[216:219], v[226:227], off offset:128
	global_load_dwordx4 v[204:207], v[234:235], off offset:128
	global_load_dwordx4 v[220:223], v[226:227], off offset:192
	global_load_dwordx4 v[244:247], v[234:235], off offset:192
	s_waitcnt vmcnt(0)
	v_pk_mul_f32 v[92:93], v[92:93], v[116:117]
	v_pk_add_f32 v[154:155], v[154:155], v[132:133] op_sel_hi:[1,0] neg_lo:[0,1] neg_hi:[0,1]
	v_pk_mul_f32 v[94:95], v[94:95], v[118:119]
	v_pk_add_f32 v[156:157], v[156:157], v[132:133] op_sel_hi:[1,0] neg_lo:[0,1] neg_hi:[0,1]
	v_pk_mul_f32 v[154:155], v[154:155], v[132:133] op_sel:[0,1] op_sel_hi:[1,1]
	v_pk_mul_f32 v[156:157], v[156:157], v[132:133] op_sel:[0,1] op_sel_hi:[1,1]
	v_pk_fma_f32 v[154:155], v[96:97], v[154:155], v[112:113]
	v_pk_fma_f32 v[156:157], v[98:99], v[156:157], v[114:115]
	v_pk_fma_f32 v[92:93], v[154:155], s[8:9], v[92:93] op_sel_hi:[1,0,1]
	v_pk_fma_f32 v[94:95], v[156:157], s[8:9], v[94:95] op_sel_hi:[1,0,1]
	global_store_dwordx4 v[228:229], v[92:95], off
	v_pk_mul_f32 v[88:89], v[88:89], v[120:121]
	v_pk_add_f32 v[158:159], v[158:159], v[132:133] op_sel_hi:[1,0] neg_lo:[0,1] neg_hi:[0,1]
	v_pk_mul_f32 v[90:91], v[90:91], v[122:123]
	v_pk_add_f32 v[160:161], v[160:161], v[132:133] op_sel_hi:[1,0] neg_lo:[0,1] neg_hi:[0,1]
	v_pk_mul_f32 v[158:159], v[158:159], v[132:133] op_sel:[0,1] op_sel_hi:[1,1]
	v_pk_mul_f32 v[160:161], v[160:161], v[132:133] op_sel:[0,1] op_sel_hi:[1,1]
	v_pk_fma_f32 v[158:159], v[100:101], v[158:159], v[150:151]
	v_pk_fma_f32 v[160:161], v[102:103], v[160:161], v[152:153]
	v_pk_fma_f32 v[88:89], v[158:159], s[8:9], v[88:89] op_sel_hi:[1,0,1]
	v_pk_fma_f32 v[90:91], v[160:161], s[8:9], v[90:91] op_sel_hi:[1,0,1]
	global_store_dwordx4 v[228:229], v[88:91], off offset:64
	v_pk_mul_f32 v[84:85], v[84:85], v[124:125]
	v_pk_add_f32 v[162:163], v[162:163], v[132:133] op_sel_hi:[1,0] neg_lo:[0,1] neg_hi:[0,1]
	v_pk_mul_f32 v[86:87], v[86:87], v[126:127]
	v_pk_add_f32 v[164:165], v[164:165], v[132:133] op_sel_hi:[1,0] neg_lo:[0,1] neg_hi:[0,1]
	v_pk_mul_f32 v[162:163], v[162:163], v[132:133] op_sel:[0,1] op_sel_hi:[1,1]
	v_pk_mul_f32 v[164:165], v[164:165], v[132:133] op_sel:[0,1] op_sel_hi:[1,1]
	v_pk_fma_f32 v[162:163], v[104:105], v[162:163], v[142:143]
	v_pk_fma_f32 v[164:165], v[106:107], v[164:165], v[144:145]
	v_pk_fma_f32 v[84:85], v[162:163], s[8:9], v[84:85] op_sel_hi:[1,0,1]
	v_pk_fma_f32 v[86:87], v[164:165], s[8:9], v[86:87] op_sel_hi:[1,0,1]
	global_store_dwordx4 v[228:229], v[84:87], off offset:128
	v_pk_mul_f32 v[80:81], v[80:81], v[134:135]
	v_pk_add_f32 v[166:167], v[166:167], v[132:133] op_sel_hi:[1,0] neg_lo:[0,1] neg_hi:[0,1]
	v_pk_mul_f32 v[82:83], v[82:83], v[136:137]
	v_pk_add_f32 v[168:169], v[168:169], v[132:133] op_sel_hi:[1,0] neg_lo:[0,1] neg_hi:[0,1]
	v_pk_mul_f32 v[166:167], v[166:167], v[132:133] op_sel:[0,1] op_sel_hi:[1,1]
	v_pk_mul_f32 v[168:169], v[168:169], v[132:133] op_sel:[0,1] op_sel_hi:[1,1]
	v_pk_fma_f32 v[166:167], v[108:109], v[166:167], v[146:147]
	v_pk_fma_f32 v[168:169], v[110:111], v[168:169], v[148:149]
	v_pk_fma_f32 v[80:81], v[166:167], s[8:9], v[80:81] op_sel_hi:[1,0,1]
	v_pk_fma_f32 v[82:83], v[168:169], s[8:9], v[82:83] op_sel_hi:[1,0,1]
	global_store_dwordx4 v[228:229], v[80:83], off offset:192
	v_pk_mul_f32 v[76:77], v[76:77], v[138:139]
	v_pk_add_f32 v[208:209], v[208:209], v[128:129] op_sel_hi:[1,0] neg_lo:[0,1] neg_hi:[0,1]
	v_pk_mul_f32 v[78:79], v[78:79], v[140:141]
	v_pk_add_f32 v[210:211], v[210:211], v[128:129] op_sel_hi:[1,0] neg_lo:[0,1] neg_hi:[0,1]
	v_pk_mul_f32 v[208:209], v[208:209], v[170:171] op_sel_hi:[1,0]
	v_pk_mul_f32 v[210:211], v[210:211], v[170:171] op_sel_hi:[1,0]
	v_pk_fma_f32 v[208:209], v[96:97], v[208:209], v[112:113]
	v_pk_fma_f32 v[210:211], v[98:99], v[210:211], v[114:115]
	v_pk_fma_f32 v[76:77], v[208:209], s[8:9], v[76:77] op_sel_hi:[1,0,1]
	v_pk_fma_f32 v[78:79], v[210:211], s[8:9], v[78:79] op_sel_hi:[1,0,1]
	global_store_dwordx4 v[230:231], v[76:79], off
	v_pk_mul_f32 v[72:73], v[72:73], v[200:201]
	v_pk_add_f32 v[212:213], v[212:213], v[128:129] op_sel_hi:[1,0] neg_lo:[0,1] neg_hi:[0,1]
	v_pk_mul_f32 v[74:75], v[74:75], v[202:203]
	v_pk_add_f32 v[214:215], v[214:215], v[128:129] op_sel_hi:[1,0] neg_lo:[0,1] neg_hi:[0,1]
	v_pk_mul_f32 v[212:213], v[212:213], v[170:171] op_sel_hi:[1,0]
	v_pk_mul_f32 v[214:215], v[214:215], v[170:171] op_sel_hi:[1,0]
	v_pk_fma_f32 v[212:213], v[100:101], v[212:213], v[150:151]
	v_pk_fma_f32 v[214:215], v[102:103], v[214:215], v[152:153]
	v_pk_fma_f32 v[72:73], v[212:213], s[8:9], v[72:73] op_sel_hi:[1,0,1]
	v_pk_fma_f32 v[74:75], v[214:215], s[8:9], v[74:75] op_sel_hi:[1,0,1]
	global_store_dwordx4 v[230:231], v[72:75], off offset:64
	v_pk_mul_f32 v[68:69], v[68:69], v[204:205]
	v_pk_add_f32 v[216:217], v[216:217], v[128:129] op_sel_hi:[1,0] neg_lo:[0,1] neg_hi:[0,1]
	v_pk_mul_f32 v[70:71], v[70:71], v[206:207]
	v_pk_add_f32 v[218:219], v[218:219], v[128:129] op_sel_hi:[1,0] neg_lo:[0,1] neg_hi:[0,1]
	v_pk_mul_f32 v[216:217], v[216:217], v[170:171] op_sel_hi:[1,0]
	v_pk_mul_f32 v[218:219], v[218:219], v[170:171] op_sel_hi:[1,0]
	v_pk_fma_f32 v[216:217], v[104:105], v[216:217], v[142:143]
	v_pk_fma_f32 v[218:219], v[106:107], v[218:219], v[144:145]
	v_pk_fma_f32 v[68:69], v[216:217], s[8:9], v[68:69] op_sel_hi:[1,0,1]
	v_pk_fma_f32 v[70:71], v[218:219], s[8:9], v[70:71] op_sel_hi:[1,0,1]
	global_store_dwordx4 v[230:231], v[68:71], off offset:128
	v_pk_mul_f32 v[64:65], v[64:65], v[244:245]
	v_pk_add_f32 v[220:221], v[220:221], v[128:129] op_sel_hi:[1,0] neg_lo:[0,1] neg_hi:[0,1]
	v_pk_mul_f32 v[66:67], v[66:67], v[246:247]
	v_pk_add_f32 v[222:223], v[222:223], v[128:129] op_sel_hi:[1,0] neg_lo:[0,1] neg_hi:[0,1]
	v_pk_mul_f32 v[220:221], v[220:221], v[170:171] op_sel_hi:[1,0]
	v_pk_mul_f32 v[222:223], v[222:223], v[170:171] op_sel_hi:[1,0]
	v_pk_fma_f32 v[220:221], v[108:109], v[220:221], v[146:147]
	v_pk_fma_f32 v[222:223], v[110:111], v[222:223], v[148:149]
	v_pk_fma_f32 v[64:65], v[220:221], s[8:9], v[64:65] op_sel_hi:[1,0,1]
	v_pk_fma_f32 v[66:67], v[222:223], s[8:9], v[66:67] op_sel_hi:[1,0,1]
	global_store_dwordx4 v[230:231], v[64:67], off offset:192
	v_add_u32_e32 v254, 32, v237
	v_add_u32_e32 v236, 0xfffff000, v254
	v_cmp_lt_i32_e32 vcc, 0xfff, v254
	v_lshrrev_b32_e32 v236, 10, v236
	v_lshlrev_b32_e32 v224, 3, v254
	v_lshlrev_b32_e32 v254, 12, v254
	v_add_u32_e32 v236, 1, v236
	v_mov_b32_e32 v225, 0
	v_cndmask_b32_e32 v236, 0, v236, vcc
	v_lshl_add_u64 v[224:225], v[224:225], 0, s[10:11]
	v_lshl_add_u64 v[228:229], v[254:255], 0, v[250:251]
	v_add_u32_e32 v236, s4, v236
	v_mad_i64_i32 v[232:233], s[0:1], v236, s33, v[252:253]
	global_load_dwordx2 v[132:133], v[224:225], off
	v_lshl_add_u64 v[224:225], v[254:255], 0, v[248:249]
	v_add_u32_e32 v254, 48, v237
	v_add_u32_e32 v236, 0xfffff000, v254
	v_cmp_lt_i32_e32 vcc, 0xfff, v254
	v_lshrrev_b32_e32 v236, 10, v236
	v_lshlrev_b32_e32 v226, 3, v254
	v_lshlrev_b32_e32 v254, 12, v254
	v_add_u32_e32 v236, 1, v236
	v_mov_b32_e32 v227, 0
	v_cndmask_b32_e32 v236, 0, v236, vcc
	v_lshl_add_u64 v[226:227], v[226:227], 0, s[10:11]
	v_lshl_add_u64 v[230:231], v[254:255], 0, v[250:251]
	v_add_u32_e32 v236, s4, v236
	v_mad_i64_i32 v[234:235], s[0:1], v236, s33, v[252:253]
	global_load_dword v128, v[226:227], off
	global_load_dword v170, v[226:227], off offset:4
	v_lshl_add_u64 v[226:227], v[254:255], 0, v[248:249]
	global_load_dwordx4 v[154:157], v[224:225], off
	global_load_dwordx4 v[116:119], v[232:233], off
	global_load_dwordx4 v[158:161], v[224:225], off offset:64
	global_load_dwordx4 v[120:123], v[232:233], off offset:64
	global_load_dwordx4 v[162:165], v[224:225], off offset:128
	global_load_dwordx4 v[124:127], v[232:233], off offset:128
	global_load_dwordx4 v[166:169], v[224:225], off offset:192
	global_load_dwordx4 v[134:137], v[232:233], off offset:192
	global_load_dwordx4 v[208:211], v[226:227], off
	global_load_dwordx4 v[138:141], v[234:235], off
	global_load_dwordx4 v[212:215], v[226:227], off offset:64
	global_load_dwordx4 v[200:203], v[234:235], off offset:64
	global_load_dwordx4 v[216:219], v[226:227], off offset:128
	global_load_dwordx4 v[204:207], v[234:235], off offset:128
	global_load_dwordx4 v[220:223], v[226:227], off offset:192
	global_load_dwordx4 v[244:247], v[234:235], off offset:192
	s_waitcnt vmcnt(0)
	v_pk_mul_f32 v[60:61], v[60:61], v[116:117]
	v_pk_add_f32 v[154:155], v[154:155], v[132:133] op_sel_hi:[1,0] neg_lo:[0,1] neg_hi:[0,1]
	v_pk_mul_f32 v[62:63], v[62:63], v[118:119]
	v_pk_add_f32 v[156:157], v[156:157], v[132:133] op_sel_hi:[1,0] neg_lo:[0,1] neg_hi:[0,1]
	v_pk_mul_f32 v[154:155], v[154:155], v[132:133] op_sel:[0,1] op_sel_hi:[1,1]
	v_pk_mul_f32 v[156:157], v[156:157], v[132:133] op_sel:[0,1] op_sel_hi:[1,1]
	v_pk_fma_f32 v[154:155], v[96:97], v[154:155], v[112:113]
	v_pk_fma_f32 v[156:157], v[98:99], v[156:157], v[114:115]
	v_pk_fma_f32 v[60:61], v[154:155], s[8:9], v[60:61] op_sel_hi:[1,0,1]
	v_pk_fma_f32 v[62:63], v[156:157], s[8:9], v[62:63] op_sel_hi:[1,0,1]
	global_store_dwordx4 v[228:229], v[60:63], off
	v_pk_mul_f32 v[56:57], v[56:57], v[120:121]
	v_pk_add_f32 v[158:159], v[158:159], v[132:133] op_sel_hi:[1,0] neg_lo:[0,1] neg_hi:[0,1]
	v_pk_mul_f32 v[58:59], v[58:59], v[122:123]
	v_pk_add_f32 v[160:161], v[160:161], v[132:133] op_sel_hi:[1,0] neg_lo:[0,1] neg_hi:[0,1]
	v_pk_mul_f32 v[158:159], v[158:159], v[132:133] op_sel:[0,1] op_sel_hi:[1,1]
	v_pk_mul_f32 v[160:161], v[160:161], v[132:133] op_sel:[0,1] op_sel_hi:[1,1]
	v_pk_fma_f32 v[158:159], v[100:101], v[158:159], v[150:151]
	v_pk_fma_f32 v[160:161], v[102:103], v[160:161], v[152:153]
	v_pk_fma_f32 v[56:57], v[158:159], s[8:9], v[56:57] op_sel_hi:[1,0,1]
	v_pk_fma_f32 v[58:59], v[160:161], s[8:9], v[58:59] op_sel_hi:[1,0,1]
	global_store_dwordx4 v[228:229], v[56:59], off offset:64
	v_pk_mul_f32 v[52:53], v[52:53], v[124:125]
	v_pk_add_f32 v[162:163], v[162:163], v[132:133] op_sel_hi:[1,0] neg_lo:[0,1] neg_hi:[0,1]
	v_pk_mul_f32 v[54:55], v[54:55], v[126:127]
	v_pk_add_f32 v[164:165], v[164:165], v[132:133] op_sel_hi:[1,0] neg_lo:[0,1] neg_hi:[0,1]
	v_pk_mul_f32 v[162:163], v[162:163], v[132:133] op_sel:[0,1] op_sel_hi:[1,1]
	v_pk_mul_f32 v[164:165], v[164:165], v[132:133] op_sel:[0,1] op_sel_hi:[1,1]
	v_pk_fma_f32 v[162:163], v[104:105], v[162:163], v[142:143]
	v_pk_fma_f32 v[164:165], v[106:107], v[164:165], v[144:145]
	v_pk_fma_f32 v[52:53], v[162:163], s[8:9], v[52:53] op_sel_hi:[1,0,1]
	v_pk_fma_f32 v[54:55], v[164:165], s[8:9], v[54:55] op_sel_hi:[1,0,1]
	global_store_dwordx4 v[228:229], v[52:55], off offset:128
	v_pk_mul_f32 v[48:49], v[48:49], v[134:135]
	v_pk_add_f32 v[166:167], v[166:167], v[132:133] op_sel_hi:[1,0] neg_lo:[0,1] neg_hi:[0,1]
	v_pk_mul_f32 v[50:51], v[50:51], v[136:137]
	v_pk_add_f32 v[168:169], v[168:169], v[132:133] op_sel_hi:[1,0] neg_lo:[0,1] neg_hi:[0,1]
	v_pk_mul_f32 v[166:167], v[166:167], v[132:133] op_sel:[0,1] op_sel_hi:[1,1]
	v_pk_mul_f32 v[168:169], v[168:169], v[132:133] op_sel:[0,1] op_sel_hi:[1,1]
	v_pk_fma_f32 v[166:167], v[108:109], v[166:167], v[146:147]
	v_pk_fma_f32 v[168:169], v[110:111], v[168:169], v[148:149]
	v_pk_fma_f32 v[48:49], v[166:167], s[8:9], v[48:49] op_sel_hi:[1,0,1]
	v_pk_fma_f32 v[50:51], v[168:169], s[8:9], v[50:51] op_sel_hi:[1,0,1]
	global_store_dwordx4 v[228:229], v[48:51], off offset:192
	v_pk_mul_f32 v[44:45], v[44:45], v[138:139]
	v_pk_add_f32 v[208:209], v[208:209], v[128:129] op_sel_hi:[1,0] neg_lo:[0,1] neg_hi:[0,1]
	v_pk_mul_f32 v[46:47], v[46:47], v[140:141]
	v_pk_add_f32 v[210:211], v[210:211], v[128:129] op_sel_hi:[1,0] neg_lo:[0,1] neg_hi:[0,1]
	v_pk_mul_f32 v[208:209], v[208:209], v[170:171] op_sel_hi:[1,0]
	v_pk_mul_f32 v[210:211], v[210:211], v[170:171] op_sel_hi:[1,0]
	v_pk_fma_f32 v[208:209], v[96:97], v[208:209], v[112:113]
	v_pk_fma_f32 v[210:211], v[98:99], v[210:211], v[114:115]
	v_pk_fma_f32 v[44:45], v[208:209], s[8:9], v[44:45] op_sel_hi:[1,0,1]
	v_pk_fma_f32 v[46:47], v[210:211], s[8:9], v[46:47] op_sel_hi:[1,0,1]
	global_store_dwordx4 v[230:231], v[44:47], off
	v_pk_mul_f32 v[40:41], v[40:41], v[200:201]
	v_pk_add_f32 v[212:213], v[212:213], v[128:129] op_sel_hi:[1,0] neg_lo:[0,1] neg_hi:[0,1]
	v_pk_mul_f32 v[42:43], v[42:43], v[202:203]
	v_pk_add_f32 v[214:215], v[214:215], v[128:129] op_sel_hi:[1,0] neg_lo:[0,1] neg_hi:[0,1]
	v_pk_mul_f32 v[212:213], v[212:213], v[170:171] op_sel_hi:[1,0]
	v_pk_mul_f32 v[214:215], v[214:215], v[170:171] op_sel_hi:[1,0]
	v_pk_fma_f32 v[212:213], v[100:101], v[212:213], v[150:151]
	v_pk_fma_f32 v[214:215], v[102:103], v[214:215], v[152:153]
	v_pk_fma_f32 v[40:41], v[212:213], s[8:9], v[40:41] op_sel_hi:[1,0,1]
	v_pk_fma_f32 v[42:43], v[214:215], s[8:9], v[42:43] op_sel_hi:[1,0,1]
	global_store_dwordx4 v[230:231], v[40:43], off offset:64
	v_pk_mul_f32 v[36:37], v[36:37], v[204:205]
	v_pk_add_f32 v[216:217], v[216:217], v[128:129] op_sel_hi:[1,0] neg_lo:[0,1] neg_hi:[0,1]
	v_pk_mul_f32 v[38:39], v[38:39], v[206:207]
	v_pk_add_f32 v[218:219], v[218:219], v[128:129] op_sel_hi:[1,0] neg_lo:[0,1] neg_hi:[0,1]
	v_pk_mul_f32 v[216:217], v[216:217], v[170:171] op_sel_hi:[1,0]
	v_pk_mul_f32 v[218:219], v[218:219], v[170:171] op_sel_hi:[1,0]
	v_pk_fma_f32 v[216:217], v[104:105], v[216:217], v[142:143]
	v_pk_fma_f32 v[218:219], v[106:107], v[218:219], v[144:145]
	v_pk_fma_f32 v[36:37], v[216:217], s[8:9], v[36:37] op_sel_hi:[1,0,1]
	v_pk_fma_f32 v[38:39], v[218:219], s[8:9], v[38:39] op_sel_hi:[1,0,1]
	global_store_dwordx4 v[230:231], v[36:39], off offset:128
	v_pk_mul_f32 v[32:33], v[32:33], v[244:245]
	v_pk_add_f32 v[220:221], v[220:221], v[128:129] op_sel_hi:[1,0] neg_lo:[0,1] neg_hi:[0,1]
	v_pk_mul_f32 v[34:35], v[34:35], v[246:247]
	v_pk_add_f32 v[222:223], v[222:223], v[128:129] op_sel_hi:[1,0] neg_lo:[0,1] neg_hi:[0,1]
	v_pk_mul_f32 v[220:221], v[220:221], v[170:171] op_sel_hi:[1,0]
	v_pk_mul_f32 v[222:223], v[222:223], v[170:171] op_sel_hi:[1,0]
	v_pk_fma_f32 v[220:221], v[108:109], v[220:221], v[146:147]
	v_pk_fma_f32 v[222:223], v[110:111], v[222:223], v[148:149]
	v_pk_fma_f32 v[32:33], v[220:221], s[8:9], v[32:33] op_sel_hi:[1,0,1]
	v_pk_fma_f32 v[34:35], v[222:223], s[8:9], v[34:35] op_sel_hi:[1,0,1]
	global_store_dwordx4 v[230:231], v[32:35], off offset:192
	v_add_u32_e32 v254, 64, v237
	v_add_u32_e32 v236, 0xfffff000, v254
	v_cmp_lt_i32_e32 vcc, 0xfff, v254
	v_lshrrev_b32_e32 v236, 10, v236
	v_lshlrev_b32_e32 v224, 3, v254
	v_lshlrev_b32_e32 v254, 12, v254
	v_add_u32_e32 v236, 1, v236
	v_mov_b32_e32 v225, 0
	v_cndmask_b32_e32 v236, 0, v236, vcc
	v_lshl_add_u64 v[224:225], v[224:225], 0, s[10:11]
	v_lshl_add_u64 v[228:229], v[254:255], 0, v[250:251]
	v_add_u32_e32 v236, s4, v236
	v_mad_i64_i32 v[232:233], s[0:1], v236, s33, v[252:253]
	global_load_dwordx2 v[132:133], v[224:225], off
	v_lshl_add_u64 v[224:225], v[254:255], 0, v[248:249]
	v_add_u32_e32 v254, 80, v237
	v_add_u32_e32 v236, 0xfffff000, v254
	v_cmp_lt_i32_e32 vcc, 0xfff, v254
	v_lshrrev_b32_e32 v236, 10, v236
	v_lshlrev_b32_e32 v226, 3, v254
	v_lshlrev_b32_e32 v254, 12, v254
	v_add_u32_e32 v236, 1, v236
	v_mov_b32_e32 v227, 0
	v_cndmask_b32_e32 v236, 0, v236, vcc
	v_lshl_add_u64 v[226:227], v[226:227], 0, s[10:11]
	v_lshl_add_u64 v[230:231], v[254:255], 0, v[250:251]
	v_add_u32_e32 v236, s4, v236
	v_mad_i64_i32 v[234:235], s[0:1], v236, s33, v[252:253]
	global_load_dword v128, v[226:227], off
	global_load_dword v170, v[226:227], off offset:4
	v_lshl_add_u64 v[226:227], v[254:255], 0, v[248:249]
	global_load_dwordx4 v[154:157], v[224:225], off
	global_load_dwordx4 v[116:119], v[232:233], off
	global_load_dwordx4 v[158:161], v[224:225], off offset:64
	global_load_dwordx4 v[120:123], v[232:233], off offset:64
	global_load_dwordx4 v[162:165], v[224:225], off offset:128
	global_load_dwordx4 v[124:127], v[232:233], off offset:128
	global_load_dwordx4 v[166:169], v[224:225], off offset:192
	global_load_dwordx4 v[134:137], v[232:233], off offset:192
	global_load_dwordx4 v[208:211], v[226:227], off
	global_load_dwordx4 v[138:141], v[234:235], off
	global_load_dwordx4 v[212:215], v[226:227], off offset:64
	global_load_dwordx4 v[200:203], v[234:235], off offset:64
	global_load_dwordx4 v[216:219], v[226:227], off offset:128
	global_load_dwordx4 v[204:207], v[234:235], off offset:128
	global_load_dwordx4 v[220:223], v[226:227], off offset:192
	global_load_dwordx4 v[244:247], v[234:235], off offset:192
	s_waitcnt vmcnt(0)
	v_pk_mul_f32 v[28:29], v[28:29], v[116:117]
	v_pk_add_f32 v[154:155], v[154:155], v[132:133] op_sel_hi:[1,0] neg_lo:[0,1] neg_hi:[0,1]
	v_pk_mul_f32 v[30:31], v[30:31], v[118:119]
	v_pk_add_f32 v[156:157], v[156:157], v[132:133] op_sel_hi:[1,0] neg_lo:[0,1] neg_hi:[0,1]
	v_pk_mul_f32 v[154:155], v[154:155], v[132:133] op_sel:[0,1] op_sel_hi:[1,1]
	v_pk_mul_f32 v[156:157], v[156:157], v[132:133] op_sel:[0,1] op_sel_hi:[1,1]
	v_pk_fma_f32 v[154:155], v[96:97], v[154:155], v[112:113]
	v_pk_fma_f32 v[156:157], v[98:99], v[156:157], v[114:115]
	v_pk_fma_f32 v[28:29], v[154:155], s[8:9], v[28:29] op_sel_hi:[1,0,1]
	v_pk_fma_f32 v[30:31], v[156:157], s[8:9], v[30:31] op_sel_hi:[1,0,1]
	global_store_dwordx4 v[228:229], v[28:31], off
	v_pk_mul_f32 v[24:25], v[24:25], v[120:121]
	v_pk_add_f32 v[158:159], v[158:159], v[132:133] op_sel_hi:[1,0] neg_lo:[0,1] neg_hi:[0,1]
	v_pk_mul_f32 v[26:27], v[26:27], v[122:123]
	v_pk_add_f32 v[160:161], v[160:161], v[132:133] op_sel_hi:[1,0] neg_lo:[0,1] neg_hi:[0,1]
	v_pk_mul_f32 v[158:159], v[158:159], v[132:133] op_sel:[0,1] op_sel_hi:[1,1]
	v_pk_mul_f32 v[160:161], v[160:161], v[132:133] op_sel:[0,1] op_sel_hi:[1,1]
	v_pk_fma_f32 v[158:159], v[100:101], v[158:159], v[150:151]
	v_pk_fma_f32 v[160:161], v[102:103], v[160:161], v[152:153]
	v_pk_fma_f32 v[24:25], v[158:159], s[8:9], v[24:25] op_sel_hi:[1,0,1]
	v_pk_fma_f32 v[26:27], v[160:161], s[8:9], v[26:27] op_sel_hi:[1,0,1]
	global_store_dwordx4 v[228:229], v[24:27], off offset:64
	v_pk_mul_f32 v[20:21], v[20:21], v[124:125]
	v_pk_add_f32 v[162:163], v[162:163], v[132:133] op_sel_hi:[1,0] neg_lo:[0,1] neg_hi:[0,1]
	v_pk_mul_f32 v[22:23], v[22:23], v[126:127]
	v_pk_add_f32 v[164:165], v[164:165], v[132:133] op_sel_hi:[1,0] neg_lo:[0,1] neg_hi:[0,1]
	v_pk_mul_f32 v[162:163], v[162:163], v[132:133] op_sel:[0,1] op_sel_hi:[1,1]
	v_pk_mul_f32 v[164:165], v[164:165], v[132:133] op_sel:[0,1] op_sel_hi:[1,1]
	v_pk_fma_f32 v[162:163], v[104:105], v[162:163], v[142:143]
	v_pk_fma_f32 v[164:165], v[106:107], v[164:165], v[144:145]
	v_pk_fma_f32 v[20:21], v[162:163], s[8:9], v[20:21] op_sel_hi:[1,0,1]
	v_pk_fma_f32 v[22:23], v[164:165], s[8:9], v[22:23] op_sel_hi:[1,0,1]
	global_store_dwordx4 v[228:229], v[20:23], off offset:128
	v_pk_mul_f32 v[16:17], v[16:17], v[134:135]
	v_pk_add_f32 v[166:167], v[166:167], v[132:133] op_sel_hi:[1,0] neg_lo:[0,1] neg_hi:[0,1]
	v_pk_mul_f32 v[18:19], v[18:19], v[136:137]
	v_pk_add_f32 v[168:169], v[168:169], v[132:133] op_sel_hi:[1,0] neg_lo:[0,1] neg_hi:[0,1]
	v_pk_mul_f32 v[166:167], v[166:167], v[132:133] op_sel:[0,1] op_sel_hi:[1,1]
	v_pk_mul_f32 v[168:169], v[168:169], v[132:133] op_sel:[0,1] op_sel_hi:[1,1]
	v_pk_fma_f32 v[166:167], v[108:109], v[166:167], v[146:147]
	v_pk_fma_f32 v[168:169], v[110:111], v[168:169], v[148:149]
	v_pk_fma_f32 v[16:17], v[166:167], s[8:9], v[16:17] op_sel_hi:[1,0,1]
	v_pk_fma_f32 v[18:19], v[168:169], s[8:9], v[18:19] op_sel_hi:[1,0,1]
	global_store_dwordx4 v[228:229], v[16:19], off offset:192
	v_pk_mul_f32 v[8:9], v[8:9], v[138:139]
	v_pk_add_f32 v[208:209], v[208:209], v[128:129] op_sel_hi:[1,0] neg_lo:[0,1] neg_hi:[0,1]
	v_pk_mul_f32 v[10:11], v[10:11], v[140:141]
	v_pk_add_f32 v[210:211], v[210:211], v[128:129] op_sel_hi:[1,0] neg_lo:[0,1] neg_hi:[0,1]
	v_pk_mul_f32 v[208:209], v[208:209], v[170:171] op_sel_hi:[1,0]
	v_pk_mul_f32 v[210:211], v[210:211], v[170:171] op_sel_hi:[1,0]
	v_pk_fma_f32 v[208:209], v[96:97], v[208:209], v[112:113]
	v_pk_fma_f32 v[210:211], v[98:99], v[210:211], v[114:115]
	v_pk_fma_f32 v[8:9], v[208:209], s[8:9], v[8:9] op_sel_hi:[1,0,1]
	v_pk_fma_f32 v[10:11], v[210:211], s[8:9], v[10:11] op_sel_hi:[1,0,1]
	global_store_dwordx4 v[230:231], v[8:11], off
	v_pk_mul_f32 v[4:5], v[4:5], v[200:201]
	v_pk_add_f32 v[212:213], v[212:213], v[128:129] op_sel_hi:[1,0] neg_lo:[0,1] neg_hi:[0,1]
	v_pk_mul_f32 v[6:7], v[6:7], v[202:203]
	v_pk_add_f32 v[214:215], v[214:215], v[128:129] op_sel_hi:[1,0] neg_lo:[0,1] neg_hi:[0,1]
	v_pk_mul_f32 v[212:213], v[212:213], v[170:171] op_sel_hi:[1,0]
	v_pk_mul_f32 v[214:215], v[214:215], v[170:171] op_sel_hi:[1,0]
	v_pk_fma_f32 v[212:213], v[100:101], v[212:213], v[150:151]
	v_pk_fma_f32 v[214:215], v[102:103], v[214:215], v[152:153]
	v_pk_fma_f32 v[4:5], v[212:213], s[8:9], v[4:5] op_sel_hi:[1,0,1]
	v_pk_fma_f32 v[6:7], v[214:215], s[8:9], v[6:7] op_sel_hi:[1,0,1]
	global_store_dwordx4 v[230:231], v[4:7], off offset:64
	v_pk_mul_f32 v[12:13], v[12:13], v[204:205]
	v_pk_add_f32 v[216:217], v[216:217], v[128:129] op_sel_hi:[1,0] neg_lo:[0,1] neg_hi:[0,1]
	v_pk_mul_f32 v[14:15], v[14:15], v[206:207]
	v_pk_add_f32 v[218:219], v[218:219], v[128:129] op_sel_hi:[1,0] neg_lo:[0,1] neg_hi:[0,1]
	v_pk_mul_f32 v[216:217], v[216:217], v[170:171] op_sel_hi:[1,0]
	v_pk_mul_f32 v[218:219], v[218:219], v[170:171] op_sel_hi:[1,0]
	v_pk_fma_f32 v[216:217], v[104:105], v[216:217], v[142:143]
	v_pk_fma_f32 v[218:219], v[106:107], v[218:219], v[144:145]
	v_pk_fma_f32 v[12:13], v[216:217], s[8:9], v[12:13] op_sel_hi:[1,0,1]
	v_pk_fma_f32 v[14:15], v[218:219], s[8:9], v[14:15] op_sel_hi:[1,0,1]
	global_store_dwordx4 v[230:231], v[12:15], off offset:128
	v_pk_mul_f32 v[0:1], v[0:1], v[244:245]
	v_pk_add_f32 v[220:221], v[220:221], v[128:129] op_sel_hi:[1,0] neg_lo:[0,1] neg_hi:[0,1]
	v_pk_mul_f32 v[2:3], v[2:3], v[246:247]
	v_pk_add_f32 v[222:223], v[222:223], v[128:129] op_sel_hi:[1,0] neg_lo:[0,1] neg_hi:[0,1]
	v_pk_mul_f32 v[220:221], v[220:221], v[170:171] op_sel_hi:[1,0]
	v_pk_mul_f32 v[222:223], v[222:223], v[170:171] op_sel_hi:[1,0]
	v_pk_fma_f32 v[220:221], v[108:109], v[220:221], v[146:147]
	v_pk_fma_f32 v[222:223], v[110:111], v[222:223], v[148:149]
	v_pk_fma_f32 v[0:1], v[220:221], s[8:9], v[0:1] op_sel_hi:[1,0,1]
	v_pk_fma_f32 v[2:3], v[222:223], s[8:9], v[2:3] op_sel_hi:[1,0,1]
	global_store_dwordx4 v[230:231], v[0:3], off offset:192
	v_readlane_b32 s9, v242, 26
	v_readlane_b32 s10, v242, 27
	v_readlane_b32 s11, v242, 28
	v_readlane_b32 s12, v242, 29
	v_readlane_b32 s13, v242, 30
	v_readlane_b32 s14, v242, 31
	v_readlane_b32 s15, v242, 32
	v_readlane_b32 s16, v242, 33
	v_readlane_b32 s17, v242, 34
	v_readlane_b32 s18, v242, 35
	v_readlane_b32 s19, v242, 36
	v_readlane_b32 s20, v242, 37
	v_readlane_b32 s21, v242, 38
	v_readlane_b32 s22, v242, 39
	v_readlane_b32 s23, v242, 40
	s_mov_b64 s[24:25], 0x5000
	s_movk_i32 s6, 0xfff
	s_waitcnt lgkmcnt(0)
	s_barrier
	s_cmpk_gt_i32 s5, 0xff
	s_cbranch_scc0 .LBB0_52

.Lk_out:
	s_waitcnt lgkmcnt(0)
	v_mfma_f32_16x16x32_bf16 v[92:95], v[166:169], v[134:137], v[92:95]
	s_waitcnt vmcnt(10)
	s_barrier
	v_mfma_f32_16x16x32_bf16 v[88:91], v[200:203], v[134:137], v[88:91]
	s_cmp_eq_u32 s35, 0xf000
	s_cselect_b32 s38, s37, s36
	s_add_u32 s39, s34, s35
	v_mfma_f32_16x16x32_bf16 v[84:87], v[204:207], v[134:137], v[84:87]
	v_add_u32_e32 v170, s38, v170
	v_add_u32_e32 v172, s38, v172
	s_add_u32 s35, s35, s38
	v_mfma_f32_16x16x32_bf16 v[80:83], v[208:211], v[134:137], v[80:83]
	ds_read_b128 v[212:215], v170
	ds_read_b128 v[216:219], v170 offset:1024
	v_mfma_f32_16x16x32_bf16 v[76:79], v[166:169], v[138:141], v[76:79]
	ds_read_b128 v[220:223], v170 offset:2048
	ds_read_b128 v[224:227], v170 offset:3072
	v_mfma_f32_16x16x32_bf16 v[72:75], v[200:203], v[138:141], v[72:75]
	ds_read_b128 v[228:231], v170 offset:4096
	ds_read_b128 v[232:235], v170 offset:5120
	v_mfma_f32_16x16x32_bf16 v[68:71], v[204:207], v[138:141], v[68:71]
	ds_read_b128 v[244:247], v172 offset:12288
	ds_read_b128 v[248:251], v172 offset:13312
	v_mfma_f32_16x16x32_bf16 v[64:67], v[208:211], v[138:141], v[64:67]
	ds_read_b128 v[252:255], v172 offset:14336
	ds_read_b128 v[116:119], v172 offset:15360
	v_mfma_f32_16x16x32_bf16 v[60:63], v[166:169], v[150:153], v[60:63]
	s_mov_b32 m0, s39
	v_mfma_f32_16x16x32_bf16 v[56:59], v[200:203], v[150:153], v[56:59]
	global_load_lds_dwordx4 v[124:125], off
	v_lshl_add_u64 v[124:125], v[124:125], 0, 64
	v_mfma_f32_16x16x32_bf16 v[52:55], v[204:207], v[150:153], v[52:55]
	s_add_u32 m0, s39, 0x1000
	v_mfma_f32_16x16x32_bf16 v[48:51], v[208:211], v[150:153], v[48:51]
	global_load_lds_dwordx4 v[122:123], off
	v_lshl_add_u64 v[122:123], v[122:123], 0, 64
	v_mfma_f32_16x16x32_bf16 v[44:47], v[166:169], v[154:157], v[44:47]
	s_add_u32 m0, s39, 0x2000
	v_mfma_f32_16x16x32_bf16 v[40:43], v[200:203], v[154:157], v[40:43]
	global_load_lds_dwordx4 v[120:121], off
	v_lshl_add_u64 v[120:121], v[120:121], 0, 64
	v_mfma_f32_16x16x32_bf16 v[36:39], v[204:207], v[154:157], v[36:39]
	s_add_u32 m0, s39, 0x3000
	v_mfma_f32_16x16x32_bf16 v[32:35], v[208:211], v[154:157], v[32:35]
	global_load_lds_dwordx4 v[236:237], off
	v_lshl_add_u64 v[236:237], v[236:237], 0, 64
	v_mfma_f32_16x16x32_bf16 v[28:31], v[166:169], v[158:161], v[28:31]
	s_add_u32 m0, s39, 0x4000
	v_mfma_f32_16x16x32_bf16 v[24:27], v[200:203], v[158:161], v[24:27]
	global_load_lds_dwordx4 v[126:127], off
	v_lshl_add_u64 v[126:127], v[126:127], 0, 64
	v_mfma_f32_16x16x32_bf16 v[20:23], v[204:207], v[158:161], v[20:23]
	v_mfma_f32_16x16x32_bf16 v[16:19], v[208:211], v[158:161], v[16:19]
	v_mfma_f32_16x16x32_bf16 v[8:11], v[166:169], v[162:165], v[8:11]
	v_mfma_f32_16x16x32_bf16 v[4:7], v[200:203], v[162:165], v[4:7]
	v_mfma_f32_16x16x32_bf16 v[12:15], v[204:207], v[162:165], v[12:15]
	v_mfma_f32_16x16x32_bf16 v[0:3], v[208:211], v[162:165], v[0:3]
	s_waitcnt lgkmcnt(0)
	v_mfma_f32_16x16x32_bf16 v[92:95], v[244:247], v[212:215], v[92:95]
	s_waitcnt vmcnt(10)
	s_barrier
	v_mfma_f32_16x16x32_bf16 v[88:91], v[248:251], v[212:215], v[88:91]
	s_cmp_eq_u32 s35, 0xf000
	s_cselect_b32 s38, s37, s36
	s_add_u32 s39, s34, s35
	v_mfma_f32_16x16x32_bf16 v[84:87], v[252:255], v[212:215], v[84:87]
	v_add_u32_e32 v170, s38, v170
	v_add_u32_e32 v172, s38, v172
	s_add_u32 s35, s35, s38
	v_mfma_f32_16x16x32_bf16 v[80:83], v[116:119], v[212:215], v[80:83]
	ds_read_b128 v[134:137], v170
	ds_read_b128 v[138:141], v170 offset:1024
	v_mfma_f32_16x16x32_bf16 v[76:79], v[244:247], v[216:219], v[76:79]
	ds_read_b128 v[150:153], v170 offset:2048
	ds_read_b128 v[154:157], v170 offset:3072
	v_mfma_f32_16x16x32_bf16 v[72:75], v[248:251], v[216:219], v[72:75]
	ds_read_b128 v[158:161], v170 offset:4096
	ds_read_b128 v[162:165], v170 offset:5120
	v_mfma_f32_16x16x32_bf16 v[68:71], v[252:255], v[216:219], v[68:71]
	ds_read_b128 v[166:169], v172 offset:12288
	ds_read_b128 v[200:203], v172 offset:13312
	v_mfma_f32_16x16x32_bf16 v[64:67], v[116:119], v[216:219], v[64:67]
	ds_read_b128 v[204:207], v172 offset:14336
	ds_read_b128 v[208:211], v172 offset:15360
	v_mfma_f32_16x16x32_bf16 v[60:63], v[244:247], v[220:223], v[60:63]
	s_mov_b32 m0, s39
	v_mfma_f32_16x16x32_bf16 v[56:59], v[248:251], v[220:223], v[56:59]
	global_load_lds_dwordx4 v[124:125], off
	v_lshl_add_u64 v[124:125], v[124:125], 0, 64
	v_mfma_f32_16x16x32_bf16 v[52:55], v[252:255], v[220:223], v[52:55]
	s_add_u32 m0, s39, 0x1000
	v_mfma_f32_16x16x32_bf16 v[48:51], v[116:119], v[220:223], v[48:51]
	global_load_lds_dwordx4 v[122:123], off
	v_lshl_add_u64 v[122:123], v[122:123], 0, 64
	v_mfma_f32_16x16x32_bf16 v[44:47], v[244:247], v[224:227], v[44:47]
	s_add_u32 m0, s39, 0x2000
	v_mfma_f32_16x16x32_bf16 v[40:43], v[248:251], v[224:227], v[40:43]
	global_load_lds_dwordx4 v[120:121], off
	v_lshl_add_u64 v[120:121], v[120:121], 0, 64
	v_mfma_f32_16x16x32_bf16 v[36:39], v[252:255], v[224:227], v[36:39]
	s_add_u32 m0, s39, 0x3000
	v_mfma_f32_16x16x32_bf16 v[32:35], v[116:119], v[224:227], v[32:35]
	global_load_lds_dwordx4 v[236:237], off
	v_lshl_add_u64 v[236:237], v[236:237], 0, 64
	v_mfma_f32_16x16x32_bf16 v[28:31], v[244:247], v[228:231], v[28:31]
	s_add_u32 m0, s39, 0x4000
	v_mfma_f32_16x16x32_bf16 v[24:27], v[248:251], v[228:231], v[24:27]
	global_load_lds_dwordx4 v[126:127], off
	v_lshl_add_u64 v[126:127], v[126:127], 0, 64
	v_mfma_f32_16x16x32_bf16 v[20:23], v[252:255], v[228:231], v[20:23]
	s_add_i32 s41, s41, -1
	s_cmp_eq_u32 s41, 0
	v_mfma_f32_16x16x32_bf16 v[16:19], v[116:119], v[228:231], v[16:19]
	v_mfma_f32_16x16x32_bf16 v[8:11], v[244:247], v[232:235], v[8:11]
	v_mfma_f32_16x16x32_bf16 v[4:7], v[248:251], v[232:235], v[4:7]
	v_mfma_f32_16x16x32_bf16 v[12:15], v[252:255], v[232:235], v[12:15]
	v_mfma_f32_16x16x32_bf16 v[0:3], v[116:119], v[232:235], v[0:3]
	s_cbranch_scc0 .Lk_out
	s_waitcnt lgkmcnt(0)
	v_mfma_f32_16x16x32_bf16 v[92:95], v[166:169], v[134:137], v[92:95]
	s_waitcnt vmcnt(10)
	s_barrier
	v_mfma_f32_16x16x32_bf16 v[88:91], v[200:203], v[134:137], v[88:91]
	s_cmp_eq_u32 s35, 0xf000
	s_cselect_b32 s38, s37, s36
	v_mfma_f32_16x16x32_bf16 v[84:87], v[204:207], v[134:137], v[84:87]
	v_add_u32_e32 v170, s38, v170
	v_add_u32_e32 v172, s38, v172
	s_add_u32 s35, s35, s38
	v_mfma_f32_16x16x32_bf16 v[80:83], v[208:211], v[134:137], v[80:83]
	ds_read_b128 v[212:215], v170
	ds_read_b128 v[216:219], v170 offset:1024
	v_mfma_f32_16x16x32_bf16 v[76:79], v[166:169], v[138:141], v[76:79]
	ds_read_b128 v[220:223], v170 offset:2048
	ds_read_b128 v[224:227], v170 offset:3072
	v_mfma_f32_16x16x32_bf16 v[72:75], v[200:203], v[138:141], v[72:75]
	ds_read_b128 v[228:231], v170 offset:4096
	ds_read_b128 v[232:235], v170 offset:5120
	v_mfma_f32_16x16x32_bf16 v[68:71], v[204:207], v[138:141], v[68:71]
	ds_read_b128 v[244:247], v172 offset:12288
	ds_read_b128 v[248:251], v172 offset:13312
	v_mfma_f32_16x16x32_bf16 v[64:67], v[208:211], v[138:141], v[64:67]
	ds_read_b128 v[252:255], v172 offset:14336
	ds_read_b128 v[116:119], v172 offset:15360
	v_mfma_f32_16x16x32_bf16 v[60:63], v[166:169], v[150:153], v[60:63]
	v_mfma_f32_16x16x32_bf16 v[56:59], v[200:203], v[150:153], v[56:59]
	v_mfma_f32_16x16x32_bf16 v[52:55], v[204:207], v[150:153], v[52:55]
	v_mfma_f32_16x16x32_bf16 v[48:51], v[208:211], v[150:153], v[48:51]
	v_mfma_f32_16x16x32_bf16 v[44:47], v[166:169], v[154:157], v[44:47]
	v_mfma_f32_16x16x32_bf16 v[40:43], v[200:203], v[154:157], v[40:43]
	v_mfma_f32_16x16x32_bf16 v[36:39], v[204:207], v[154:157], v[36:39]
	v_mfma_f32_16x16x32_bf16 v[32:35], v[208:211], v[154:157], v[32:35]
	v_mfma_f32_16x16x32_bf16 v[28:31], v[166:169], v[158:161], v[28:31]
	v_mfma_f32_16x16x32_bf16 v[24:27], v[200:203], v[158:161], v[24:27]
	v_mfma_f32_16x16x32_bf16 v[20:23], v[204:207], v[158:161], v[20:23]
	v_mfma_f32_16x16x32_bf16 v[16:19], v[208:211], v[158:161], v[16:19]
	v_mfma_f32_16x16x32_bf16 v[8:11], v[166:169], v[162:165], v[8:11]
	v_mfma_f32_16x16x32_bf16 v[4:7], v[200:203], v[162:165], v[4:7]
	v_mfma_f32_16x16x32_bf16 v[12:15], v[204:207], v[162:165], v[12:15]
	v_mfma_f32_16x16x32_bf16 v[0:3], v[208:211], v[162:165], v[0:3]
	s_waitcnt lgkmcnt(0)
	v_mfma_f32_16x16x32_bf16 v[92:95], v[244:247], v[212:215], v[92:95]
	s_waitcnt vmcnt(5)
	s_barrier
	v_mfma_f32_16x16x32_bf16 v[88:91], v[248:251], v[212:215], v[88:91]
	s_cmp_eq_u32 s35, 0xf000
	s_cselect_b32 s38, s37, s36
	v_mfma_f32_16x16x32_bf16 v[84:87], v[252:255], v[212:215], v[84:87]
	v_add_u32_e32 v170, s38, v170
	v_add_u32_e32 v172, s38, v172
	s_add_u32 s35, s35, s38
	v_mfma_f32_16x16x32_bf16 v[80:83], v[116:119], v[212:215], v[80:83]
	ds_read_b128 v[134:137], v170
	ds_read_b128 v[138:141], v170 offset:1024
	v_mfma_f32_16x16x32_bf16 v[76:79], v[244:247], v[216:219], v[76:79]
	ds_read_b128 v[150:153], v170 offset:2048
	ds_read_b128 v[154:157], v170 offset:3072
	v_mfma_f32_16x16x32_bf16 v[72:75], v[248:251], v[216:219], v[72:75]
	ds_read_b128 v[158:161], v170 offset:4096
	ds_read_b128 v[162:165], v170 offset:5120
	v_mfma_f32_16x16x32_bf16 v[68:71], v[252:255], v[216:219], v[68:71]
	ds_read_b128 v[166:169], v172 offset:12288
	ds_read_b128 v[200:203], v172 offset:13312
	v_mfma_f32_16x16x32_bf16 v[64:67], v[116:119], v[216:219], v[64:67]
	ds_read_b128 v[204:207], v172 offset:14336
	ds_read_b128 v[208:211], v172 offset:15360
	v_mfma_f32_16x16x32_bf16 v[60:63], v[244:247], v[220:223], v[60:63]
	v_mfma_f32_16x16x32_bf16 v[56:59], v[248:251], v[220:223], v[56:59]
	v_mfma_f32_16x16x32_bf16 v[52:55], v[252:255], v[220:223], v[52:55]
	v_mfma_f32_16x16x32_bf16 v[48:51], v[116:119], v[220:223], v[48:51]
	v_mfma_f32_16x16x32_bf16 v[44:47], v[244:247], v[224:227], v[44:47]
	v_mfma_f32_16x16x32_bf16 v[40:43], v[248:251], v[224:227], v[40:43]
	v_mfma_f32_16x16x32_bf16 v[36:39], v[252:255], v[224:227], v[36:39]
	v_mfma_f32_16x16x32_bf16 v[32:35], v[116:119], v[224:227], v[32:35]
	v_mfma_f32_16x16x32_bf16 v[28:31], v[244:247], v[228:231], v[28:31]
	v_mfma_f32_16x16x32_bf16 v[24:27], v[248:251], v[228:231], v[24:27]
	v_mfma_f32_16x16x32_bf16 v[20:23], v[252:255], v[228:231], v[20:23]
	v_mfma_f32_16x16x32_bf16 v[16:19], v[116:119], v[228:231], v[16:19]
	v_mfma_f32_16x16x32_bf16 v[8:11], v[244:247], v[232:235], v[8:11]
	v_mfma_f32_16x16x32_bf16 v[4:7], v[248:251], v[232:235], v[4:7]
	v_mfma_f32_16x16x32_bf16 v[12:15], v[252:255], v[232:235], v[12:15]
	v_mfma_f32_16x16x32_bf16 v[0:3], v[116:119], v[232:235], v[0:3]
	s_waitcnt lgkmcnt(0)
	v_mfma_f32_16x16x32_bf16 v[92:95], v[166:169], v[134:137], v[92:95]
	s_waitcnt vmcnt(0)
	s_barrier
	v_mfma_f32_16x16x32_bf16 v[88:91], v[200:203], v[134:137], v[88:91]
	s_cmp_eq_u32 s35, 0xf000
	s_cselect_b32 s38, s37, s36
	v_mfma_f32_16x16x32_bf16 v[84:87], v[204:207], v[134:137], v[84:87]
	v_add_u32_e32 v170, s38, v170
	v_add_u32_e32 v172, s38, v172
	s_add_u32 s35, s35, s38
	v_mfma_f32_16x16x32_bf16 v[80:83], v[208:211], v[134:137], v[80:83]
	ds_read_b128 v[212:215], v170
	ds_read_b128 v[216:219], v170 offset:1024
	v_mfma_f32_16x16x32_bf16 v[76:79], v[166:169], v[138:141], v[76:79]
	ds_read_b128 v[220:223], v170 offset:2048
	ds_read_b128 v[224:227], v170 offset:3072
	v_mfma_f32_16x16x32_bf16 v[72:75], v[200:203], v[138:141], v[72:75]
	ds_read_b128 v[228:231], v170 offset:4096
	ds_read_b128 v[232:235], v170 offset:5120
	v_mfma_f32_16x16x32_bf16 v[68:71], v[204:207], v[138:141], v[68:71]
	ds_read_b128 v[244:247], v172 offset:12288
	ds_read_b128 v[248:251], v172 offset:13312
	v_mfma_f32_16x16x32_bf16 v[64:67], v[208:211], v[138:141], v[64:67]
	ds_read_b128 v[252:255], v172 offset:14336
	ds_read_b128 v[116:119], v172 offset:15360
	v_mfma_f32_16x16x32_bf16 v[60:63], v[166:169], v[150:153], v[60:63]
	v_mfma_f32_16x16x32_bf16 v[56:59], v[200:203], v[150:153], v[56:59]
	v_mfma_f32_16x16x32_bf16 v[52:55], v[204:207], v[150:153], v[52:55]
	v_mfma_f32_16x16x32_bf16 v[48:51], v[208:211], v[150:153], v[48:51]
	v_mfma_f32_16x16x32_bf16 v[44:47], v[166:169], v[154:157], v[44:47]
	v_mfma_f32_16x16x32_bf16 v[40:43], v[200:203], v[154:157], v[40:43]
	v_mfma_f32_16x16x32_bf16 v[36:39], v[204:207], v[154:157], v[36:39]
	v_mfma_f32_16x16x32_bf16 v[32:35], v[208:211], v[154:157], v[32:35]
	v_mfma_f32_16x16x32_bf16 v[28:31], v[166:169], v[158:161], v[28:31]
	v_mfma_f32_16x16x32_bf16 v[24:27], v[200:203], v[158:161], v[24:27]
	v_mfma_f32_16x16x32_bf16 v[20:23], v[204:207], v[158:161], v[20:23]
	v_mfma_f32_16x16x32_bf16 v[16:19], v[208:211], v[158:161], v[16:19]
	v_mfma_f32_16x16x32_bf16 v[8:11], v[166:169], v[162:165], v[8:11]
	v_mfma_f32_16x16x32_bf16 v[4:7], v[200:203], v[162:165], v[4:7]
	v_mfma_f32_16x16x32_bf16 v[12:15], v[204:207], v[162:165], v[12:15]
	v_mfma_f32_16x16x32_bf16 v[0:3], v[208:211], v[162:165], v[0:3]
	s_waitcnt lgkmcnt(0)
	v_mfma_f32_16x16x32_bf16 v[92:95], v[244:247], v[212:215], v[92:95]
	v_mfma_f32_16x16x32_bf16 v[88:91], v[248:251], v[212:215], v[88:91]
	v_mfma_f32_16x16x32_bf16 v[84:87], v[252:255], v[212:215], v[84:87]
	v_mfma_f32_16x16x32_bf16 v[80:83], v[116:119], v[212:215], v[80:83]
	v_mfma_f32_16x16x32_bf16 v[76:79], v[244:247], v[216:219], v[76:79]
	v_mfma_f32_16x16x32_bf16 v[72:75], v[248:251], v[216:219], v[72:75]
	v_mfma_f32_16x16x32_bf16 v[68:71], v[252:255], v[216:219], v[68:71]
	v_mfma_f32_16x16x32_bf16 v[64:67], v[116:119], v[216:219], v[64:67]
	v_mfma_f32_16x16x32_bf16 v[60:63], v[244:247], v[220:223], v[60:63]
	v_mfma_f32_16x16x32_bf16 v[56:59], v[248:251], v[220:223], v[56:59]
	v_mfma_f32_16x16x32_bf16 v[52:55], v[252:255], v[220:223], v[52:55]
	v_mfma_f32_16x16x32_bf16 v[48:51], v[116:119], v[220:223], v[48:51]
	v_mfma_f32_16x16x32_bf16 v[44:47], v[244:247], v[224:227], v[44:47]
	v_mfma_f32_16x16x32_bf16 v[40:43], v[248:251], v[224:227], v[40:43]
	v_mfma_f32_16x16x32_bf16 v[36:39], v[252:255], v[224:227], v[36:39]
	v_mfma_f32_16x16x32_bf16 v[32:35], v[116:119], v[224:227], v[32:35]
	v_mfma_f32_16x16x32_bf16 v[28:31], v[244:247], v[228:231], v[28:31]
	v_mfma_f32_16x16x32_bf16 v[24:27], v[248:251], v[228:231], v[24:27]
	v_mfma_f32_16x16x32_bf16 v[20:23], v[252:255], v[228:231], v[20:23]
	v_mfma_f32_16x16x32_bf16 v[16:19], v[116:119], v[228:231], v[16:19]
	v_mfma_f32_16x16x32_bf16 v[8:11], v[244:247], v[232:235], v[8:11]
	v_mfma_f32_16x16x32_bf16 v[4:7], v[248:251], v[232:235], v[4:7]
	v_mfma_f32_16x16x32_bf16 v[12:15], v[252:255], v[232:235], v[12:15]
	v_mfma_f32_16x16x32_bf16 v[0:3], v[116:119], v[232:235], v[0:3]
	s_barrier
	v_mov_b32_e32 v170, s46
	v_mov_b32_e32 v172, s47
	ds_write_b32 v183, v170
	ds_write_b32 v184, v172
	s_waitcnt lgkmcnt(0)
	s_add_i32 s9, s9, s51
	v_readlane_b32 s10, v241, 9
	s_cmp_eq_u32 s10, 7
	s_cbranch_scc0 .Lout_epi_ln
	v_readlane_b32 s10, v243, 21
	v_readlane_b32 s11, v243, 22
	v_readlane_b32 s12, v242, 29
	v_readlane_b32 s13, v242, 30
	v_readlane_b32 s14, v243, 11
	v_readlane_b32 s15, v243, 12
	s_mov_b32 s6, 0x3fd744fd
	v_add_u32_e32 v236, s0, v145
	v_or_b32_e32 v254, s4, v146
	v_mov_b32_e32 v255, 0
	v_or_b32_e32 v237, v236, v133
	v_lshlrev_b64 v[254:255], 2, v[254:255]
	s_nop 0
	v_lshl_add_u64 v[248:249], s[10:11], 0, v[254:255]
	v_lshl_add_u64 v[250:251], s[12:13], 0, v[254:255]
	v_lshl_add_u64 v[252:253], s[14:15], 0, v[254:255]
	s_mov_b64 s[10:11], 0x2000
	v_mov_b32_e32 v255, 0
	v_lshl_add_u64 v[252:253], v[252:253], 0, s[10:11]
	v_readlane_b32 s10, v243, 21
	v_readlane_b32 s11, v243, 22
	v_readlane_b32 s12, v243, 23
	v_readlane_b32 s13, v243, 24
	s_sub_u32 s12, s12, s10
	s_subb_u32 s13, s13, s11
	s_sub_u32 s12, s12, 0x1000000
	s_subb_u32 s13, s13, 0
	v_add_u32_e32 v254, 0, v237
	v_add_u32_e32 v236, 0xfffff000, v254
	v_cmp_lt_i32_e32 vcc, 0xfff, v254
	v_lshrrev_b32_e32 v236, 10, v236
	v_lshlrev_b32_e32 v254, 12, v254
	v_add_u32_e32 v236, 1, v236
	v_cndmask_b32_e32 v236, 0, v236, vcc
	v_lshl_add_u64 v[224:225], v[254:255], 0, v[248:249]
	v_lshl_add_u64 v[228:229], v[254:255], 0, v[250:251]
	v_add_u32_e32 v236, s8, v236
	v_mad_i64_i32 v[232:233], s[0:1], v236, s33, v[252:253]
	v_mov_b32_e32 v236, s12
	v_mov_b32_e32 v254, s13
	v_cndmask_b32_e32 v236, 0, v236, vcc
	v_cndmask_b32_e32 v254, 0, v254, vcc
	v_add_co_u32_e32 v224, vcc, v224, v236
	s_nop 0
	v_addc_co_u32_e32 v225, vcc, v225, v254, vcc
	v_add_u32_e32 v254, 16, v237
	v_add_u32_e32 v236, 0xfffff000, v254
	v_cmp_lt_i32_e32 vcc, 0xfff, v254
	v_lshrrev_b32_e32 v236, 10, v236
	v_lshlrev_b32_e32 v254, 12, v254
	v_add_u32_e32 v236, 1, v236
	v_cndmask_b32_e32 v236, 0, v236, vcc
	v_lshl_add_u64 v[226:227], v[254:255], 0, v[248:249]
	v_lshl_add_u64 v[230:231], v[254:255], 0, v[250:251]
	v_add_u32_e32 v236, s8, v236
	v_mad_i64_i32 v[234:235], s[0:1], v236, s33, v[252:253]
	v_mov_b32_e32 v236, s12
	v_mov_b32_e32 v254, s13
	v_cndmask_b32_e32 v236, 0, v236, vcc
	v_cndmask_b32_e32 v254, 0, v254, vcc
	v_add_co_u32_e32 v226, vcc, v226, v236
	s_nop 0
	v_addc_co_u32_e32 v227, vcc, v227, v254, vcc
	global_load_dwordx4 v[154:157], v[224:225], off
	global_load_dwordx4 v[116:119], v[232:233], off
	global_load_dwordx4 v[158:161], v[224:225], off offset:64
	global_load_dwordx4 v[120:123], v[232:233], off offset:64
	global_load_dwordx4 v[162:165], v[224:225], off offset:128
	global_load_dwordx4 v[124:127], v[232:233], off offset:128
	global_load_dwordx4 v[166:169], v[224:225], off offset:192
	global_load_dwordx4 v[134:137], v[232:233], off offset:192
	global_load_dwordx4 v[208:211], v[226:227], off
	global_load_dwordx4 v[138:141], v[234:235], off
	global_load_dwordx4 v[212:215], v[226:227], off offset:64
	global_load_dwordx4 v[200:203], v[234:235], off offset:64
	global_load_dwordx4 v[216:219], v[226:227], off offset:128
	global_load_dwordx4 v[204:207], v[234:235], off offset:128
	global_load_dwordx4 v[220:223], v[226:227], off offset:192
	global_load_dwordx4 v[244:247], v[234:235], off offset:192
	s_waitcnt vmcnt(0)
	v_pk_mul_f32 v[92:93], v[92:93], v[116:117]
	v_pk_mul_f32 v[94:95], v[94:95], v[118:119]
	v_pk_fma_f32 v[92:93], v[154:155], s[6:7], v[92:93] op_sel_hi:[1,0,1]
	v_pk_fma_f32 v[94:95], v[156:157], s[6:7], v[94:95] op_sel_hi:[1,0,1]
	global_store_dwordx4 v[228:229], v[92:95], off
	v_pk_mul_f32 v[88:89], v[88:89], v[120:121]
	v_pk_mul_f32 v[90:91], v[90:91], v[122:123]
	v_pk_fma_f32 v[88:89], v[158:159], s[6:7], v[88:89] op_sel_hi:[1,0,1]
	v_pk_fma_f32 v[90:91], v[160:161], s[6:7], v[90:91] op_sel_hi:[1,0,1]
	global_store_dwordx4 v[228:229], v[88:91], off offset:64
	v_pk_mul_f32 v[84:85], v[84:85], v[124:125]
	v_pk_mul_f32 v[86:87], v[86:87], v[126:127]
	v_pk_fma_f32 v[84:85], v[162:163], s[6:7], v[84:85] op_sel_hi:[1,0,1]
	v_pk_fma_f32 v[86:87], v[164:165], s[6:7], v[86:87] op_sel_hi:[1,0,1]
	global_store_dwordx4 v[228:229], v[84:87], off offset:128
	v_pk_mul_f32 v[80:81], v[80:81], v[134:135]
	v_pk_mul_f32 v[82:83], v[82:83], v[136:137]
	v_pk_fma_f32 v[80:81], v[166:167], s[6:7], v[80:81] op_sel_hi:[1,0,1]
	v_pk_fma_f32 v[82:83], v[168:169], s[6:7], v[82:83] op_sel_hi:[1,0,1]
	global_store_dwordx4 v[228:229], v[80:83], off offset:192
	v_pk_mul_f32 v[76:77], v[76:77], v[138:139]
	v_pk_mul_f32 v[78:79], v[78:79], v[140:141]
	v_pk_fma_f32 v[76:77], v[208:209], s[6:7], v[76:77] op_sel_hi:[1,0,1]
	v_pk_fma_f32 v[78:79], v[210:211], s[6:7], v[78:79] op_sel_hi:[1,0,1]
	global_store_dwordx4 v[230:231], v[76:79], off
	v_pk_mul_f32 v[72:73], v[72:73], v[200:201]
	v_pk_mul_f32 v[74:75], v[74:75], v[202:203]
	v_pk_fma_f32 v[72:73], v[212:213], s[6:7], v[72:73] op_sel_hi:[1,0,1]
	v_pk_fma_f32 v[74:75], v[214:215], s[6:7], v[74:75] op_sel_hi:[1,0,1]
	global_store_dwordx4 v[230:231], v[72:75], off offset:64
	v_pk_mul_f32 v[68:69], v[68:69], v[204:205]
	v_pk_mul_f32 v[70:71], v[70:71], v[206:207]
	v_pk_fma_f32 v[68:69], v[216:217], s[6:7], v[68:69] op_sel_hi:[1,0,1]
	v_pk_fma_f32 v[70:71], v[218:219], s[6:7], v[70:71] op_sel_hi:[1,0,1]
	global_store_dwordx4 v[230:231], v[68:71], off offset:128
	v_pk_mul_f32 v[64:65], v[64:65], v[244:245]
	v_pk_mul_f32 v[66:67], v[66:67], v[246:247]
	v_pk_fma_f32 v[64:65], v[220:221], s[6:7], v[64:65] op_sel_hi:[1,0,1]
	v_pk_fma_f32 v[66:67], v[222:223], s[6:7], v[66:67] op_sel_hi:[1,0,1]
	global_store_dwordx4 v[230:231], v[64:67], off offset:192
	v_add_u32_e32 v254, 32, v237
	v_add_u32_e32 v236, 0xfffff000, v254
	v_cmp_lt_i32_e32 vcc, 0xfff, v254
	v_lshrrev_b32_e32 v236, 10, v236
	v_lshlrev_b32_e32 v254, 12, v254
	v_add_u32_e32 v236, 1, v236
	v_cndmask_b32_e32 v236, 0, v236, vcc
	v_lshl_add_u64 v[224:225], v[254:255], 0, v[248:249]
	v_lshl_add_u64 v[228:229], v[254:255], 0, v[250:251]
	v_add_u32_e32 v236, s8, v236
	v_mad_i64_i32 v[232:233], s[0:1], v236, s33, v[252:253]
	v_mov_b32_e32 v236, s12
	v_mov_b32_e32 v254, s13
	v_cndmask_b32_e32 v236, 0, v236, vcc
	v_cndmask_b32_e32 v254, 0, v254, vcc
	v_add_co_u32_e32 v224, vcc, v224, v236
	s_nop 0
	v_addc_co_u32_e32 v225, vcc, v225, v254, vcc
	v_add_u32_e32 v254, 48, v237
	v_add_u32_e32 v236, 0xfffff000, v254
	v_cmp_lt_i32_e32 vcc, 0xfff, v254
	v_lshrrev_b32_e32 v236, 10, v236
	v_lshlrev_b32_e32 v254, 12, v254
	v_add_u32_e32 v236, 1, v236
	v_cndmask_b32_e32 v236, 0, v236, vcc
	v_lshl_add_u64 v[226:227], v[254:255], 0, v[248:249]
	v_lshl_add_u64 v[230:231], v[254:255], 0, v[250:251]
	v_add_u32_e32 v236, s8, v236
	v_mad_i64_i32 v[234:235], s[0:1], v236, s33, v[252:253]
	v_mov_b32_e32 v236, s12
	v_mov_b32_e32 v254, s13
	v_cndmask_b32_e32 v236, 0, v236, vcc
	v_cndmask_b32_e32 v254, 0, v254, vcc
	v_add_co_u32_e32 v226, vcc, v226, v236
	s_nop 0
	v_addc_co_u32_e32 v227, vcc, v227, v254, vcc
	global_load_dwordx4 v[154:157], v[224:225], off
	global_load_dwordx4 v[116:119], v[232:233], off
	global_load_dwordx4 v[158:161], v[224:225], off offset:64
	global_load_dwordx4 v[120:123], v[232:233], off offset:64
	global_load_dwordx4 v[162:165], v[224:225], off offset:128
	global_load_dwordx4 v[124:127], v[232:233], off offset:128
	global_load_dwordx4 v[166:169], v[224:225], off offset:192
	global_load_dwordx4 v[134:137], v[232:233], off offset:192
	global_load_dwordx4 v[208:211], v[226:227], off
	global_load_dwordx4 v[138:141], v[234:235], off
	global_load_dwordx4 v[212:215], v[226:227], off offset:64
	global_load_dwordx4 v[200:203], v[234:235], off offset:64
	global_load_dwordx4 v[216:219], v[226:227], off offset:128
	global_load_dwordx4 v[204:207], v[234:235], off offset:128
	global_load_dwordx4 v[220:223], v[226:227], off offset:192
	global_load_dwordx4 v[244:247], v[234:235], off offset:192
	s_waitcnt vmcnt(0)
	v_pk_mul_f32 v[60:61], v[60:61], v[116:117]
	v_pk_mul_f32 v[62:63], v[62:63], v[118:119]
	v_pk_fma_f32 v[60:61], v[154:155], s[6:7], v[60:61] op_sel_hi:[1,0,1]
	v_pk_fma_f32 v[62:63], v[156:157], s[6:7], v[62:63] op_sel_hi:[1,0,1]
	global_store_dwordx4 v[228:229], v[60:63], off
	v_pk_mul_f32 v[56:57], v[56:57], v[120:121]
	v_pk_mul_f32 v[58:59], v[58:59], v[122:123]
	v_pk_fma_f32 v[56:57], v[158:159], s[6:7], v[56:57] op_sel_hi:[1,0,1]
	v_pk_fma_f32 v[58:59], v[160:161], s[6:7], v[58:59] op_sel_hi:[1,0,1]
	global_store_dwordx4 v[228:229], v[56:59], off offset:64
	v_pk_mul_f32 v[52:53], v[52:53], v[124:125]
	v_pk_mul_f32 v[54:55], v[54:55], v[126:127]
	v_pk_fma_f32 v[52:53], v[162:163], s[6:7], v[52:53] op_sel_hi:[1,0,1]
	v_pk_fma_f32 v[54:55], v[164:165], s[6:7], v[54:55] op_sel_hi:[1,0,1]
	global_store_dwordx4 v[228:229], v[52:55], off offset:128
	v_pk_mul_f32 v[48:49], v[48:49], v[134:135]
	v_pk_mul_f32 v[50:51], v[50:51], v[136:137]
	v_pk_fma_f32 v[48:49], v[166:167], s[6:7], v[48:49] op_sel_hi:[1,0,1]
	v_pk_fma_f32 v[50:51], v[168:169], s[6:7], v[50:51] op_sel_hi:[1,0,1]
	global_store_dwordx4 v[228:229], v[48:51], off offset:192
	v_pk_mul_f32 v[44:45], v[44:45], v[138:139]
	v_pk_mul_f32 v[46:47], v[46:47], v[140:141]
	v_pk_fma_f32 v[44:45], v[208:209], s[6:7], v[44:45] op_sel_hi:[1,0,1]
	v_pk_fma_f32 v[46:47], v[210:211], s[6:7], v[46:47] op_sel_hi:[1,0,1]
	global_store_dwordx4 v[230:231], v[44:47], off
	v_pk_mul_f32 v[40:41], v[40:41], v[200:201]
	v_pk_mul_f32 v[42:43], v[42:43], v[202:203]
	v_pk_fma_f32 v[40:41], v[212:213], s[6:7], v[40:41] op_sel_hi:[1,0,1]
	v_pk_fma_f32 v[42:43], v[214:215], s[6:7], v[42:43] op_sel_hi:[1,0,1]
	global_store_dwordx4 v[230:231], v[40:43], off offset:64
	v_pk_mul_f32 v[36:37], v[36:37], v[204:205]
	v_pk_mul_f32 v[38:39], v[38:39], v[206:207]
	v_pk_fma_f32 v[36:37], v[216:217], s[6:7], v[36:37] op_sel_hi:[1,0,1]
	v_pk_fma_f32 v[38:39], v[218:219], s[6:7], v[38:39] op_sel_hi:[1,0,1]
	global_store_dwordx4 v[230:231], v[36:39], off offset:128
	v_pk_mul_f32 v[32:33], v[32:33], v[244:245]
	v_pk_mul_f32 v[34:35], v[34:35], v[246:247]
	v_pk_fma_f32 v[32:33], v[220:221], s[6:7], v[32:33] op_sel_hi:[1,0,1]
	v_pk_fma_f32 v[34:35], v[222:223], s[6:7], v[34:35] op_sel_hi:[1,0,1]
	global_store_dwordx4 v[230:231], v[32:35], off offset:192
	v_add_u32_e32 v254, 64, v237
	v_add_u32_e32 v236, 0xfffff000, v254
	v_cmp_lt_i32_e32 vcc, 0xfff, v254
	v_lshrrev_b32_e32 v236, 10, v236
	v_lshlrev_b32_e32 v254, 12, v254
	v_add_u32_e32 v236, 1, v236
	v_cndmask_b32_e32 v236, 0, v236, vcc
	v_lshl_add_u64 v[224:225], v[254:255], 0, v[248:249]
	v_lshl_add_u64 v[228:229], v[254:255], 0, v[250:251]
	v_add_u32_e32 v236, s8, v236
	v_mad_i64_i32 v[232:233], s[0:1], v236, s33, v[252:253]
	v_mov_b32_e32 v236, s12
	v_mov_b32_e32 v254, s13
	v_cndmask_b32_e32 v236, 0, v236, vcc
	v_cndmask_b32_e32 v254, 0, v254, vcc
	v_add_co_u32_e32 v224, vcc, v224, v236
	s_nop 0
	v_addc_co_u32_e32 v225, vcc, v225, v254, vcc
	v_add_u32_e32 v254, 80, v237
	v_add_u32_e32 v236, 0xfffff000, v254
	v_cmp_lt_i32_e32 vcc, 0xfff, v254
	v_lshrrev_b32_e32 v236, 10, v236
	v_lshlrev_b32_e32 v254, 12, v254
	v_add_u32_e32 v236, 1, v236
	v_cndmask_b32_e32 v236, 0, v236, vcc
	v_lshl_add_u64 v[226:227], v[254:255], 0, v[248:249]
	v_lshl_add_u64 v[230:231], v[254:255], 0, v[250:251]
	v_add_u32_e32 v236, s8, v236
	v_mad_i64_i32 v[234:235], s[0:1], v236, s33, v[252:253]
	v_mov_b32_e32 v236, s12
	v_mov_b32_e32 v254, s13
	v_cndmask_b32_e32 v236, 0, v236, vcc
	v_cndmask_b32_e32 v254, 0, v254, vcc
	v_add_co_u32_e32 v226, vcc, v226, v236
	s_nop 0
	v_addc_co_u32_e32 v227, vcc, v227, v254, vcc
	global_load_dwordx4 v[154:157], v[224:225], off
	global_load_dwordx4 v[116:119], v[232:233], off
	global_load_dwordx4 v[158:161], v[224:225], off offset:64
	global_load_dwordx4 v[120:123], v[232:233], off offset:64
	global_load_dwordx4 v[162:165], v[224:225], off offset:128
	global_load_dwordx4 v[124:127], v[232:233], off offset:128
	global_load_dwordx4 v[166:169], v[224:225], off offset:192
	global_load_dwordx4 v[134:137], v[232:233], off offset:192
	global_load_dwordx4 v[208:211], v[226:227], off
	global_load_dwordx4 v[138:141], v[234:235], off
	global_load_dwordx4 v[212:215], v[226:227], off offset:64
	global_load_dwordx4 v[200:203], v[234:235], off offset:64
	global_load_dwordx4 v[216:219], v[226:227], off offset:128
	global_load_dwordx4 v[204:207], v[234:235], off offset:128
	global_load_dwordx4 v[220:223], v[226:227], off offset:192
	global_load_dwordx4 v[244:247], v[234:235], off offset:192
	s_waitcnt vmcnt(0)
	v_pk_mul_f32 v[28:29], v[28:29], v[116:117]
	v_pk_mul_f32 v[30:31], v[30:31], v[118:119]
	v_pk_fma_f32 v[28:29], v[154:155], s[6:7], v[28:29] op_sel_hi:[1,0,1]
	v_pk_fma_f32 v[30:31], v[156:157], s[6:7], v[30:31] op_sel_hi:[1,0,1]
	global_store_dwordx4 v[228:229], v[28:31], off
	v_pk_mul_f32 v[24:25], v[24:25], v[120:121]
	v_pk_mul_f32 v[26:27], v[26:27], v[122:123]
	v_pk_fma_f32 v[24:25], v[158:159], s[6:7], v[24:25] op_sel_hi:[1,0,1]
	v_pk_fma_f32 v[26:27], v[160:161], s[6:7], v[26:27] op_sel_hi:[1,0,1]
	global_store_dwordx4 v[228:229], v[24:27], off offset:64
	v_pk_mul_f32 v[20:21], v[20:21], v[124:125]
	v_pk_mul_f32 v[22:23], v[22:23], v[126:127]
	v_pk_fma_f32 v[20:21], v[162:163], s[6:7], v[20:21] op_sel_hi:[1,0,1]
	v_pk_fma_f32 v[22:23], v[164:165], s[6:7], v[22:23] op_sel_hi:[1,0,1]
	global_store_dwordx4 v[228:229], v[20:23], off offset:128
	v_pk_mul_f32 v[16:17], v[16:17], v[134:135]
	v_pk_mul_f32 v[18:19], v[18:19], v[136:137]
	v_pk_fma_f32 v[16:17], v[166:167], s[6:7], v[16:17] op_sel_hi:[1,0,1]
	v_pk_fma_f32 v[18:19], v[168:169], s[6:7], v[18:19] op_sel_hi:[1,0,1]
	global_store_dwordx4 v[228:229], v[16:19], off offset:192
	v_pk_mul_f32 v[8:9], v[8:9], v[138:139]
	v_pk_mul_f32 v[10:11], v[10:11], v[140:141]
	v_pk_fma_f32 v[8:9], v[208:209], s[6:7], v[8:9] op_sel_hi:[1,0,1]
	v_pk_fma_f32 v[10:11], v[210:211], s[6:7], v[10:11] op_sel_hi:[1,0,1]
	global_store_dwordx4 v[230:231], v[8:11], off
	v_pk_mul_f32 v[4:5], v[4:5], v[200:201]
	v_pk_mul_f32 v[6:7], v[6:7], v[202:203]
	v_pk_fma_f32 v[4:5], v[212:213], s[6:7], v[4:5] op_sel_hi:[1,0,1]
	v_pk_fma_f32 v[6:7], v[214:215], s[6:7], v[6:7] op_sel_hi:[1,0,1]
	global_store_dwordx4 v[230:231], v[4:7], off offset:64
	v_pk_mul_f32 v[12:13], v[12:13], v[204:205]
	v_pk_mul_f32 v[14:15], v[14:15], v[206:207]
	v_pk_fma_f32 v[12:13], v[216:217], s[6:7], v[12:13] op_sel_hi:[1,0,1]
	v_pk_fma_f32 v[14:15], v[218:219], s[6:7], v[14:15] op_sel_hi:[1,0,1]
	global_store_dwordx4 v[230:231], v[12:15], off offset:128
	v_pk_mul_f32 v[0:1], v[0:1], v[244:245]
	v_pk_mul_f32 v[2:3], v[2:3], v[246:247]
	v_pk_fma_f32 v[0:1], v[220:221], s[6:7], v[0:1] op_sel_hi:[1,0,1]
	v_pk_fma_f32 v[2:3], v[222:223], s[6:7], v[2:3] op_sel_hi:[1,0,1]
	global_store_dwordx4 v[230:231], v[0:3], off offset:192
	s_branch .Lout_epi_done
